# EpiWin/EpiResid row-ssq xor-16/xor-32 shuffles: ds_bpermute + LDS wait replaced by v_permlane16_swap / v_permlane32_swap (48 sites)
# speedup vs baseline: 1.0077x; 1.0027x over previous
; __device__ __forceinline__ u32x4 pack8(f32x4 a, f32x4 b) { u32x4 w; w.x = pk2(a[0], a[1]); w.y = pk2(a[2], a[3]); w.z = pk2(b[0], b[1]); w.w = pk2(b[2], b[3]); return w; }
;     __device__ __forceinline__ void operator()(const Acc& acc, const Unit& u, int wr, int wc, int fr, int fq, const RsCtx& rc) const {
;     ...
;             for (int m = 0; m < 4; ++m) { const int row = EPI_ROW(u, ai, wr, m, fr);
;                 const float rs = rc.get(u.pm, ai * 128 + wr * 64 + m * 16 + fr, row);
;                 f32x4 a0 = acc[ai][0][m][0] * rs, a1 = acc[ai][0][m][1] * rs, b0 = acc[ai][1][m][0] * rs, b1 = acc[ai][1][m][1] * rs;
;                 if (pn == 0) {
;                     float s = 0.f;
; #pragma unroll
;                     for (int e = 0; e < 4; ++e) s += a0[e] * a0[e] + a1[e] * a1[e] + b0[e] * b0[e] + b1[e] * b1[e];
;                     s += __shfl_xor(s, 16); s += __shfl_xor(s, 32);
;                     if (fq == 0) ssq_q[row * 4 + wc] = s;
;                     *(u32x4*)(LAT + (size_t)row * 512 + cw) = pack8(a0, a1); *(u32x4*)(LAT + (size_t)row * 512 + 128 + cw) = pack8(b0, b1);
;                 } else if (pn == 1) {
;                     float s = 0.f;
; #pragma unroll
;                     for (int e = 0; e < 4; ++e) s += a0[e] * a0[e] + a1[e] * a1[e];
;                     s += __shfl_xor(s, 16); s += __shfl_xor(s, 32);
;                     if (fq == 0) ssq_kv[row * 4 + wc] = s;
;                     *(u32x4*)(LAT + (size_t)row * 512 + 256 + cw) = pack8(a0, a1);
.LBB0_559:
	s_cmp_gt_i32 s82, 3
	s_cselect_b64 s[4:5], -1, 0
	s_cmp_gt_u32 s82, 7
	s_mov_b32 s18, s26
	s_cselect_b64 s[26:27], -1, 0
	s_cmp_gt_u32 s82, 9
	s_waitcnt lgkmcnt(0)
	v_pk_mul_f32 v[128:129], v[128:129], v[0:1] op_sel_hi:[1,0]
	v_pk_mul_f32 v[126:127], v[126:127], v[0:1] op_sel_hi:[1,0]
	v_pk_mul_f32 v[124:125], v[124:125], v[0:1] op_sel_hi:[1,0]
	v_pk_mul_f32 v[156:157], v[122:123], v[0:1] op_sel_hi:[1,0]
	v_pk_mul_f32 v[122:123], v[120:121], v[0:1] op_sel_hi:[1,0]
	v_pk_mul_f32 v[152:153], v[118:119], v[0:1] op_sel_hi:[1,0]
	v_pk_mul_f32 v[154:155], v[116:117], v[0:1] op_sel_hi:[1,0]
	v_pk_mul_f32 v[158:159], v[114:115], v[0:1] op_sel_hi:[1,0]
	s_cselect_b64 s[16:17], -1, 0
	s_mov_b64 s[22:23], -1
	s_mov_b64 s[6:7], 0
	s_cmp_lt_i32 s82, 1
	s_mov_b64 s[24:25], 0
	s_cbranch_scc1 .LBB0_567
	s_cmp_eq_u32 s82, 1
	s_mov_b64 s[24:25], -1
	s_cbranch_scc0 .LBB0_566
	v_mul_f32_e32 v0, v156, v156
	v_mul_f32_e32 v114, v157, v157
	v_fmac_f32_e32 v0, v126, v126
	v_fmac_f32_e32 v114, v127, v127
	v_add_f32_e32 v0, v0, v114
	v_mul_f32_e32 v114, v124, v124
	v_fmac_f32_e32 v114, v128, v128
	v_add_f32_e32 v0, v114, v0
	v_mul_f32_e32 v114, v125, v125
	v_fmac_f32_e32 v114, v129, v129
	v_and_b32_e32 v115, 64, v217
	v_add_f32_e32 v0, v114, v0
	v_add_u32_e32 v115, 64, v115
	s_nop 1
	v_mov_b32_e32 v114, v0
	s_nop 1
	v_permlane16_swap_b32_e32 v114, v0
	s_waitcnt lgkmcnt(0)
	v_add_f32_e32 v0, v0, v114
	s_nop 1
	v_mov_b32_e32 v114, v0
	s_nop 1
	v_permlane32_swap_b32_e32 v114, v0
	s_and_saveexec_b64 s[22:23], s[42:43]
	s_cbranch_execz .LBB0_563
	s_waitcnt lgkmcnt(0)
	v_add_f32_e32 v0, v0, v114
	v_lshl_or_b32 v114, v150, 2, s76
	v_ashrrev_i32_e32 v115, 31, v114
	v_lshl_add_u64 v[114:115], v[114:115], 2, s[62:63]
	flat_store_dword v[114:115], v0

; __device__ __forceinline__ u32x4 pack8(f32x4 a, f32x4 b) { u32x4 w; w.x = pk2(a[0], a[1]); w.y = pk2(a[2], a[3]); w.z = pk2(b[0], b[1]); w.w = pk2(b[2], b[3]); return w; }
;     __device__ __forceinline__ void operator()(const Acc& acc, const Unit& u, int wr, int wc, int fr, int fq, const RsCtx& rc) const {
;     ...
;                 if (pn == 0) {
;                     float s = 0.f;
; #pragma unroll
;                     for (int e = 0; e < 4; ++e) s += a0[e] * a0[e] + a1[e] * a1[e] + b0[e] * b0[e] + b1[e] * b1[e];
;                     s += __shfl_xor(s, 16); s += __shfl_xor(s, 32);
;                     if (fq == 0) ssq_q[row * 4 + wc] = s;
;                     *(u32x4*)(LAT + (size_t)row * 512 + cw) = pack8(a0, a1); *(u32x4*)(LAT + (size_t)row * 512 + 128 + cw) = pack8(b0, b1);
.LBB0_583:
	s_andn2_b64 vcc, exec, s[6:7]
	s_cbranch_vccnz .LBB0_587
	v_mul_f32_e32 v114, v156, v156
	v_mul_f32_e32 v115, v157, v157
	v_fmac_f32_e32 v114, v126, v126
	v_fmac_f32_e32 v115, v127, v127
	v_fmac_f32_e32 v114, v152, v152
	v_fmac_f32_e32 v115, v153, v153
	v_fmac_f32_e32 v114, v158, v158
	v_fmac_f32_e32 v115, v159, v159
	v_add_f32_e32 v114, v114, v115
	v_mul_f32_e32 v115, v124, v124
	v_fmac_f32_e32 v115, v128, v128
	v_fmac_f32_e32 v115, v122, v122
	v_fmac_f32_e32 v115, v154, v154
	v_add_f32_e32 v114, v115, v114
	v_mul_f32_e32 v115, v125, v125
	v_fmac_f32_e32 v115, v129, v129
	v_fmac_f32_e32 v115, v123, v123
	v_fmac_f32_e32 v115, v155, v155
	v_and_b32_e32 v116, 64, v217
	v_add_f32_e32 v114, v115, v114
	v_add_u32_e32 v116, 64, v116
	s_nop 1
	v_mov_b32_e32 v115, v114
	s_nop 1
	v_permlane16_swap_b32_e32 v115, v114
	s_waitcnt lgkmcnt(0)
	v_add_f32_e32 v114, v114, v115
	s_nop 1
	v_mov_b32_e32 v115, v114
	s_nop 1
	v_permlane32_swap_b32_e32 v115, v114
	s_and_saveexec_b64 s[6:7], s[42:43]
	s_cbranch_execz .LBB0_586
	s_waitcnt lgkmcnt(0)
	v_add_f32_e32 v116, v114, v115
	v_lshl_or_b32 v114, v150, 2, s76
	v_readlane_b32 s36, v254, 54
	v_ashrrev_i32_e32 v115, 31, v114
	v_readlane_b32 s37, v254, 55
	v_readlane_b32 s38, v254, 56
	v_readlane_b32 s39, v254, 57
	v_readlane_b32 s36, v254, 44
	v_readlane_b32 s37, v254, 45
	v_lshl_add_u64 v[114:115], v[114:115], 2, s[38:39]
	v_readlane_b32 s38, v254, 48
	v_readlane_b32 s39, v254, 49
	flat_store_dword v[114:115], v116

; __device__ __forceinline__ u32x4 pack8(f32x4 a, f32x4 b) { u32x4 w; w.x = pk2(a[0], a[1]); w.y = pk2(a[2], a[3]); w.z = pk2(b[0], b[1]); w.w = pk2(b[2], b[3]); return w; }
;     __device__ __forceinline__ void operator()(const Acc& acc, const Unit& u, int wr, int wc, int fr, int fq, const RsCtx& rc) const {
;     ...
;             for (int m = 0; m < 4; ++m) { const int row = EPI_ROW(u, ai, wr, m, fr);
;                 const float rs = rc.get(u.pm, ai * 128 + wr * 64 + m * 16 + fr, row);
;                 f32x4 a0 = acc[ai][0][m][0] * rs, a1 = acc[ai][0][m][1] * rs, b0 = acc[ai][1][m][0] * rs, b1 = acc[ai][1][m][1] * rs;
;                 if (pn == 0) {
;                     float s = 0.f;
; #pragma unroll
;                     for (int e = 0; e < 4; ++e) s += a0[e] * a0[e] + a1[e] * a1[e] + b0[e] * b0[e] + b1[e] * b1[e];
;                     s += __shfl_xor(s, 16); s += __shfl_xor(s, 32);
;                     if (fq == 0) ssq_q[row * 4 + wc] = s;
;                     *(u32x4*)(LAT + (size_t)row * 512 + cw) = pack8(a0, a1); *(u32x4*)(LAT + (size_t)row * 512 + 128 + cw) = pack8(b0, b1);
;                 } else if (pn == 1) {
;                     float s = 0.f;
; #pragma unroll
;                     for (int e = 0; e < 4; ++e) s += a0[e] * a0[e] + a1[e] * a1[e];
;                     s += __shfl_xor(s, 16); s += __shfl_xor(s, 32);
;                     if (fq == 0) ssq_kv[row * 4 + wc] = s;
;                     *(u32x4*)(LAT + (size_t)row * 512 + 256 + cw) = pack8(a0, a1);
.LBB0_595:
	s_waitcnt lgkmcnt(0)
	v_pk_mul_f32 v[112:113], v[112:113], v[122:123] op_sel_hi:[1,0]
	v_pk_mul_f32 v[110:111], v[110:111], v[122:123] op_sel_hi:[1,0]
	v_pk_mul_f32 v[108:109], v[108:109], v[122:123] op_sel_hi:[1,0]
	v_pk_mul_f32 v[120:121], v[106:107], v[122:123] op_sel_hi:[1,0]
	v_pk_mul_f32 v[106:107], v[104:105], v[122:123] op_sel_hi:[1,0]
	v_pk_mul_f32 v[116:117], v[102:103], v[122:123] op_sel_hi:[1,0]
	v_pk_mul_f32 v[118:119], v[100:101], v[122:123] op_sel_hi:[1,0]
	v_pk_mul_f32 v[122:123], v[98:99], v[122:123] op_sel_hi:[1,0]
	s_mov_b64 s[28:29], -1
	s_mov_b64 s[20:21], 0
	s_cmp_lt_i32 s82, 1
	s_mov_b64 s[24:25], 0
	s_cbranch_scc1 .LBB0_623
	s_cmp_eq_u32 s82, 1
	s_mov_b64 s[24:25], -1
	s_cbranch_scc0 .LBB0_602
	v_mul_f32_e32 v98, v120, v120
	v_mul_f32_e32 v99, v121, v121
	v_fmac_f32_e32 v98, v110, v110
	v_fmac_f32_e32 v99, v111, v111
	v_add_f32_e32 v98, v98, v99
	v_mul_f32_e32 v99, v108, v108
	v_fmac_f32_e32 v99, v112, v112
	v_add_f32_e32 v98, v99, v98
	v_mul_f32_e32 v99, v109, v109
	v_fmac_f32_e32 v99, v113, v113
	v_and_b32_e32 v100, 64, v217
	v_add_f32_e32 v98, v99, v98
	v_add_u32_e32 v100, 64, v100
	s_nop 1
	v_mov_b32_e32 v99, v98
	s_nop 1
	v_permlane16_swap_b32_e32 v99, v98
	s_waitcnt lgkmcnt(0)
	v_add_f32_e32 v98, v98, v99
	s_nop 1
	v_mov_b32_e32 v99, v98
	s_nop 1
	v_permlane32_swap_b32_e32 v99, v98
	s_and_saveexec_b64 s[24:25], s[42:43]
	s_cbranch_execz .LBB0_599
	s_waitcnt lgkmcnt(0)
	v_add_f32_e32 v100, v98, v99
	v_lshl_or_b32 v98, v114, 2, s76
	v_ashrrev_i32_e32 v99, 31, v98
	v_lshl_add_u64 v[98:99], v[98:99], 2, s[62:63]
	flat_store_dword v[98:99], v100

; __device__ __forceinline__ u32x4 pack8(f32x4 a, f32x4 b) { u32x4 w; w.x = pk2(a[0], a[1]); w.y = pk2(a[2], a[3]); w.z = pk2(b[0], b[1]); w.w = pk2(b[2], b[3]); return w; }
;     __device__ __forceinline__ void operator()(const Acc& acc, const Unit& u, int wr, int wc, int fr, int fq, const RsCtx& rc) const {
;     ...
;                 if (pn == 0) {
;                     float s = 0.f;
; #pragma unroll
;                     for (int e = 0; e < 4; ++e) s += a0[e] * a0[e] + a1[e] * a1[e] + b0[e] * b0[e] + b1[e] * b1[e];
;                     s += __shfl_xor(s, 16); s += __shfl_xor(s, 32);
;                     if (fq == 0) ssq_q[row * 4 + wc] = s;
;                     *(u32x4*)(LAT + (size_t)row * 512 + cw) = pack8(a0, a1); *(u32x4*)(LAT + (size_t)row * 512 + 128 + cw) = pack8(b0, b1);
.LBB0_626:
	s_nop 0
	v_mul_f32_e32 v98, v120, v120
	v_mul_f32_e32 v99, v121, v121
	v_fmac_f32_e32 v98, v110, v110
	v_fmac_f32_e32 v99, v111, v111
	v_fmac_f32_e32 v98, v116, v116
	v_fmac_f32_e32 v99, v117, v117
	v_fmac_f32_e32 v98, v122, v122
	v_fmac_f32_e32 v99, v123, v123
	v_add_f32_e32 v98, v98, v99
	v_mul_f32_e32 v99, v108, v108
	v_fmac_f32_e32 v99, v112, v112
	v_fmac_f32_e32 v99, v106, v106
	v_fmac_f32_e32 v99, v118, v118
	v_add_f32_e32 v98, v99, v98
	v_mul_f32_e32 v99, v109, v109
	v_fmac_f32_e32 v99, v113, v113
	v_fmac_f32_e32 v99, v107, v107
	v_fmac_f32_e32 v99, v119, v119
	v_and_b32_e32 v100, 64, v217
	v_add_f32_e32 v98, v99, v98
	v_add_u32_e32 v100, 64, v100
	s_nop 1
	v_mov_b32_e32 v99, v98
	s_nop 1
	v_permlane16_swap_b32_e32 v99, v98
	s_waitcnt lgkmcnt(0)
	v_add_f32_e32 v98, v98, v99
	s_nop 1
	v_mov_b32_e32 v99, v98
	s_nop 1
	v_permlane32_swap_b32_e32 v99, v98
	s_and_saveexec_b64 s[20:21], s[42:43]
	s_cbranch_execz .LBB0_628
	s_waitcnt lgkmcnt(0)
	v_add_f32_e32 v100, v98, v99
	v_lshl_or_b32 v98, v114, 2, s76
	v_readlane_b32 s36, v254, 54
	v_ashrrev_i32_e32 v99, 31, v98
	v_readlane_b32 s37, v254, 55
	v_readlane_b32 s38, v254, 56
	v_readlane_b32 s39, v254, 57
	v_readlane_b32 s36, v254, 44
	v_readlane_b32 s37, v254, 45
	v_lshl_add_u64 v[98:99], v[98:99], 2, s[38:39]
	v_readlane_b32 s38, v254, 48
	v_readlane_b32 s39, v254, 49
	flat_store_dword v[98:99], v100

; __device__ __forceinline__ u32x4 pack8(f32x4 a, f32x4 b) { u32x4 w; w.x = pk2(a[0], a[1]); w.y = pk2(a[2], a[3]); w.z = pk2(b[0], b[1]); w.w = pk2(b[2], b[3]); return w; }
;     __device__ __forceinline__ void operator()(const Acc& acc, const Unit& u, int wr, int wc, int fr, int fq, const RsCtx& rc) const {
;     ...
;             for (int m = 0; m < 4; ++m) { const int row = EPI_ROW(u, ai, wr, m, fr);
;                 const float rs = rc.get(u.pm, ai * 128 + wr * 64 + m * 16 + fr, row);
;                 f32x4 a0 = acc[ai][0][m][0] * rs, a1 = acc[ai][0][m][1] * rs, b0 = acc[ai][1][m][0] * rs, b1 = acc[ai][1][m][1] * rs;
;                 if (pn == 0) {
;                     float s = 0.f;
; #pragma unroll
;                     for (int e = 0; e < 4; ++e) s += a0[e] * a0[e] + a1[e] * a1[e] + b0[e] * b0[e] + b1[e] * b1[e];
;                     s += __shfl_xor(s, 16); s += __shfl_xor(s, 32);
;                     if (fq == 0) ssq_q[row * 4 + wc] = s;
;                     *(u32x4*)(LAT + (size_t)row * 512 + cw) = pack8(a0, a1); *(u32x4*)(LAT + (size_t)row * 512 + 128 + cw) = pack8(b0, b1);
;                 } else if (pn == 1) {
;                     float s = 0.f;
; #pragma unroll
;                     for (int e = 0; e < 4; ++e) s += a0[e] * a0[e] + a1[e] * a1[e];
;                     s += __shfl_xor(s, 16); s += __shfl_xor(s, 32);
;                     if (fq == 0) ssq_kv[row * 4 + wc] = s;
;                     *(u32x4*)(LAT + (size_t)row * 512 + 256 + cw) = pack8(a0, a1);
.LBB0_631:
	s_waitcnt lgkmcnt(0)
	v_pk_mul_f32 v[96:97], v[96:97], v[106:107] op_sel_hi:[1,0]
	v_pk_mul_f32 v[94:95], v[94:95], v[106:107] op_sel_hi:[1,0]
	v_pk_mul_f32 v[92:93], v[92:93], v[106:107] op_sel_hi:[1,0]
	v_pk_mul_f32 v[104:105], v[90:91], v[106:107] op_sel_hi:[1,0]
	v_pk_mul_f32 v[90:91], v[88:89], v[106:107] op_sel_hi:[1,0]
	v_pk_mul_f32 v[100:101], v[86:87], v[106:107] op_sel_hi:[1,0]
	v_pk_mul_f32 v[102:103], v[84:85], v[106:107] op_sel_hi:[1,0]
	v_pk_mul_f32 v[106:107], v[82:83], v[106:107] op_sel_hi:[1,0]
	s_mov_b64 s[28:29], -1
	s_mov_b64 s[20:21], 0
	s_cmp_lt_i32 s82, 1
	s_mov_b64 s[24:25], 0
	s_cbranch_scc1 .LBB0_659
	s_cmp_eq_u32 s82, 1
	s_mov_b64 s[24:25], -1
	s_cbranch_scc0 .LBB0_638
	v_mul_f32_e32 v82, v104, v104
	v_mul_f32_e32 v83, v105, v105
	v_fmac_f32_e32 v82, v94, v94
	v_fmac_f32_e32 v83, v95, v95
	v_add_f32_e32 v82, v82, v83
	v_mul_f32_e32 v83, v92, v92
	v_fmac_f32_e32 v83, v96, v96
	v_add_f32_e32 v82, v83, v82
	v_mul_f32_e32 v83, v93, v93
	v_fmac_f32_e32 v83, v97, v97
	v_and_b32_e32 v84, 64, v217
	v_add_f32_e32 v82, v83, v82
	v_add_u32_e32 v84, 64, v84
	s_nop 1
	v_mov_b32_e32 v83, v82
	s_nop 1
	v_permlane16_swap_b32_e32 v83, v82
	s_waitcnt lgkmcnt(0)
	v_add_f32_e32 v82, v82, v83
	s_nop 1
	v_mov_b32_e32 v83, v82
	s_nop 1
	v_permlane32_swap_b32_e32 v83, v82
	s_and_saveexec_b64 s[24:25], s[42:43]
	s_cbranch_execz .LBB0_635
	s_waitcnt lgkmcnt(0)
	v_add_f32_e32 v84, v82, v83
	v_lshl_or_b32 v82, v98, 2, s76
	v_ashrrev_i32_e32 v83, 31, v82
	v_lshl_add_u64 v[82:83], v[82:83], 2, s[62:63]
	flat_store_dword v[82:83], v84

; __device__ __forceinline__ u32x4 pack8(f32x4 a, f32x4 b) { u32x4 w; w.x = pk2(a[0], a[1]); w.y = pk2(a[2], a[3]); w.z = pk2(b[0], b[1]); w.w = pk2(b[2], b[3]); return w; }
;     __device__ __forceinline__ void operator()(const Acc& acc, const Unit& u, int wr, int wc, int fr, int fq, const RsCtx& rc) const {
;     ...
;                 if (pn == 0) {
;                     float s = 0.f;
; #pragma unroll
;                     for (int e = 0; e < 4; ++e) s += a0[e] * a0[e] + a1[e] * a1[e] + b0[e] * b0[e] + b1[e] * b1[e];
;                     s += __shfl_xor(s, 16); s += __shfl_xor(s, 32);
;                     if (fq == 0) ssq_q[row * 4 + wc] = s;
;                     *(u32x4*)(LAT + (size_t)row * 512 + cw) = pack8(a0, a1); *(u32x4*)(LAT + (size_t)row * 512 + 128 + cw) = pack8(b0, b1);
.LBB0_662:
	s_nop 0
	v_mul_f32_e32 v82, v104, v104
	v_mul_f32_e32 v83, v105, v105
	v_fmac_f32_e32 v82, v94, v94
	v_fmac_f32_e32 v83, v95, v95
	v_fmac_f32_e32 v82, v100, v100
	v_fmac_f32_e32 v83, v101, v101
	v_fmac_f32_e32 v82, v106, v106
	v_fmac_f32_e32 v83, v107, v107
	v_add_f32_e32 v82, v82, v83
	v_mul_f32_e32 v83, v92, v92
	v_fmac_f32_e32 v83, v96, v96
	v_fmac_f32_e32 v83, v90, v90
	v_fmac_f32_e32 v83, v102, v102
	v_add_f32_e32 v82, v83, v82
	v_mul_f32_e32 v83, v93, v93
	v_fmac_f32_e32 v83, v97, v97
	v_fmac_f32_e32 v83, v91, v91
	v_fmac_f32_e32 v83, v103, v103
	v_and_b32_e32 v84, 64, v217
	v_add_f32_e32 v82, v83, v82
	v_add_u32_e32 v84, 64, v84
	s_nop 1
	v_mov_b32_e32 v83, v82
	s_nop 1
	v_permlane16_swap_b32_e32 v83, v82
	s_waitcnt lgkmcnt(0)
	v_add_f32_e32 v82, v82, v83
	s_nop 1
	v_mov_b32_e32 v83, v82
	s_nop 1
	v_permlane32_swap_b32_e32 v83, v82
	s_and_saveexec_b64 s[20:21], s[42:43]
	s_cbranch_execz .LBB0_664
	s_waitcnt lgkmcnt(0)
	v_add_f32_e32 v84, v82, v83
	v_lshl_or_b32 v82, v98, 2, s76
	v_readlane_b32 s36, v254, 54
	v_ashrrev_i32_e32 v83, 31, v82
	v_readlane_b32 s37, v254, 55
	v_readlane_b32 s38, v254, 56
	v_readlane_b32 s39, v254, 57
	v_readlane_b32 s36, v254, 44
	v_readlane_b32 s37, v254, 45
	v_lshl_add_u64 v[82:83], v[82:83], 2, s[38:39]
	v_readlane_b32 s38, v254, 48
	v_readlane_b32 s39, v254, 49
	flat_store_dword v[82:83], v84

; __device__ __forceinline__ u32x4 pack8(f32x4 a, f32x4 b) { u32x4 w; w.x = pk2(a[0], a[1]); w.y = pk2(a[2], a[3]); w.z = pk2(b[0], b[1]); w.w = pk2(b[2], b[3]); return w; }
;     __device__ __forceinline__ void operator()(const Acc& acc, const Unit& u, int wr, int wc, int fr, int fq, const RsCtx& rc) const {
;     ...
;             for (int m = 0; m < 4; ++m) { const int row = EPI_ROW(u, ai, wr, m, fr);
;                 const float rs = rc.get(u.pm, ai * 128 + wr * 64 + m * 16 + fr, row);
;                 f32x4 a0 = acc[ai][0][m][0] * rs, a1 = acc[ai][0][m][1] * rs, b0 = acc[ai][1][m][0] * rs, b1 = acc[ai][1][m][1] * rs;
;                 if (pn == 0) {
;                     float s = 0.f;
; #pragma unroll
;                     for (int e = 0; e < 4; ++e) s += a0[e] * a0[e] + a1[e] * a1[e] + b0[e] * b0[e] + b1[e] * b1[e];
;                     s += __shfl_xor(s, 16); s += __shfl_xor(s, 32);
;                     if (fq == 0) ssq_q[row * 4 + wc] = s;
;                     *(u32x4*)(LAT + (size_t)row * 512 + cw) = pack8(a0, a1); *(u32x4*)(LAT + (size_t)row * 512 + 128 + cw) = pack8(b0, b1);
;                 } else if (pn == 1) {
;                     float s = 0.f;
; #pragma unroll
;                     for (int e = 0; e < 4; ++e) s += a0[e] * a0[e] + a1[e] * a1[e];
;                     s += __shfl_xor(s, 16); s += __shfl_xor(s, 32);
;                     if (fq == 0) ssq_kv[row * 4 + wc] = s;
;                     *(u32x4*)(LAT + (size_t)row * 512 + 256 + cw) = pack8(a0, a1);
.LBB0_667:
	s_waitcnt lgkmcnt(0)
	v_pk_mul_f32 v[80:81], v[80:81], v[90:91] op_sel_hi:[1,0]
	v_pk_mul_f32 v[78:79], v[78:79], v[90:91] op_sel_hi:[1,0]
	v_pk_mul_f32 v[76:77], v[76:77], v[90:91] op_sel_hi:[1,0]
	v_pk_mul_f32 v[88:89], v[74:75], v[90:91] op_sel_hi:[1,0]
	v_pk_mul_f32 v[74:75], v[72:73], v[90:91] op_sel_hi:[1,0]
	v_pk_mul_f32 v[84:85], v[70:71], v[90:91] op_sel_hi:[1,0]
	v_pk_mul_f32 v[86:87], v[68:69], v[90:91] op_sel_hi:[1,0]
	v_pk_mul_f32 v[90:91], v[66:67], v[90:91] op_sel_hi:[1,0]
	s_mov_b64 s[28:29], -1
	s_mov_b64 s[20:21], 0
	s_cmp_lt_i32 s82, 1
	s_mov_b64 s[24:25], 0
	s_cbranch_scc1 .LBB0_689
	s_cmp_eq_u32 s82, 1
	s_mov_b64 s[24:25], -1
	s_cbranch_scc0 .LBB0_674
	v_mul_f32_e32 v66, v88, v88
	v_mul_f32_e32 v67, v89, v89
	v_fmac_f32_e32 v66, v78, v78
	v_fmac_f32_e32 v67, v79, v79
	v_add_f32_e32 v66, v66, v67
	v_mul_f32_e32 v67, v76, v76
	v_fmac_f32_e32 v67, v80, v80
	v_add_f32_e32 v66, v67, v66
	v_mul_f32_e32 v67, v77, v77
	v_fmac_f32_e32 v67, v81, v81
	v_and_b32_e32 v68, 64, v217
	v_add_f32_e32 v66, v67, v66
	v_add_u32_e32 v68, 64, v68
	s_nop 1
	v_mov_b32_e32 v67, v66
	s_nop 1
	v_permlane16_swap_b32_e32 v67, v66
	s_waitcnt lgkmcnt(0)
	v_add_f32_e32 v66, v66, v67
	s_nop 1
	v_mov_b32_e32 v67, v66
	s_nop 1
	v_permlane32_swap_b32_e32 v67, v66
	s_and_saveexec_b64 s[24:25], s[42:43]
	s_cbranch_execz .LBB0_671
	s_waitcnt lgkmcnt(0)
	v_add_f32_e32 v68, v66, v67
	v_lshl_or_b32 v66, v82, 2, s76
	v_ashrrev_i32_e32 v67, 31, v66
	v_lshl_add_u64 v[66:67], v[66:67], 2, s[62:63]
	flat_store_dword v[66:67], v68

; __device__ __forceinline__ u32x4 pack8(f32x4 a, f32x4 b) { u32x4 w; w.x = pk2(a[0], a[1]); w.y = pk2(a[2], a[3]); w.z = pk2(b[0], b[1]); w.w = pk2(b[2], b[3]); return w; }
;     __device__ __forceinline__ void operator()(const Acc& acc, const Unit& u, int wr, int wc, int fr, int fq, const RsCtx& rc) const {
;     ...
;                 if (pn == 0) {
;                     float s = 0.f;
; #pragma unroll
;                     for (int e = 0; e < 4; ++e) s += a0[e] * a0[e] + a1[e] * a1[e] + b0[e] * b0[e] + b1[e] * b1[e];
;                     s += __shfl_xor(s, 16); s += __shfl_xor(s, 32);
;                     if (fq == 0) ssq_q[row * 4 + wc] = s;
;                     *(u32x4*)(LAT + (size_t)row * 512 + cw) = pack8(a0, a1); *(u32x4*)(LAT + (size_t)row * 512 + 128 + cw) = pack8(b0, b1);
.LBB0_692:
	v_mul_f32_e32 v66, v88, v88
	v_mul_f32_e32 v67, v89, v89
	v_fmac_f32_e32 v66, v78, v78
	v_fmac_f32_e32 v67, v79, v79
	v_fmac_f32_e32 v66, v84, v84
	v_fmac_f32_e32 v67, v85, v85
	v_fmac_f32_e32 v66, v90, v90
	v_fmac_f32_e32 v67, v91, v91
	v_add_f32_e32 v66, v66, v67
	v_mul_f32_e32 v67, v76, v76
	v_fmac_f32_e32 v67, v80, v80
	v_fmac_f32_e32 v67, v74, v74
	v_fmac_f32_e32 v67, v86, v86
	v_add_f32_e32 v66, v67, v66
	v_mul_f32_e32 v67, v77, v77
	v_fmac_f32_e32 v67, v81, v81
	v_fmac_f32_e32 v67, v75, v75
	v_fmac_f32_e32 v67, v87, v87
	v_and_b32_e32 v68, 64, v217
	v_add_f32_e32 v66, v67, v66
	v_add_u32_e32 v68, 64, v68
	s_nop 1
	v_mov_b32_e32 v67, v66
	s_nop 1
	v_permlane16_swap_b32_e32 v67, v66
	s_waitcnt lgkmcnt(0)
	v_add_f32_e32 v66, v66, v67
	s_nop 1
	v_mov_b32_e32 v67, v66
	s_nop 1
	v_permlane32_swap_b32_e32 v67, v66
	s_and_saveexec_b64 s[20:21], s[42:43]
	s_cbranch_execz .LBB0_694
	s_waitcnt lgkmcnt(0)
	v_add_f32_e32 v68, v66, v67
	v_lshl_or_b32 v66, v82, 2, s76
	v_readlane_b32 s36, v254, 54
	v_ashrrev_i32_e32 v67, 31, v66
	v_readlane_b32 s37, v254, 55
	v_readlane_b32 s38, v254, 56
	v_readlane_b32 s39, v254, 57
	v_readlane_b32 s36, v254, 44
	v_readlane_b32 s37, v254, 45
	v_lshl_add_u64 v[66:67], v[66:67], 2, s[38:39]
	v_readlane_b32 s38, v254, 48
	v_readlane_b32 s39, v254, 49
	flat_store_dword v[66:67], v68

; __device__ __forceinline__ u32x4 pack8(f32x4 a, f32x4 b) { u32x4 w; w.x = pk2(a[0], a[1]); w.y = pk2(a[2], a[3]); w.z = pk2(b[0], b[1]); w.w = pk2(b[2], b[3]); return w; }
;     __device__ __forceinline__ void operator()(const Acc& acc, const Unit& u, int wr, int wc, int fr, int fq, const RsCtx& rc) const {
;     ...
;             for (int m = 0; m < 4; ++m) { const int row = EPI_ROW(u, ai, wr, m, fr);
;                 const float rs = rc.get(u.pm, ai * 128 + wr * 64 + m * 16 + fr, row);
;                 f32x4 a0 = acc[ai][0][m][0] * rs, a1 = acc[ai][0][m][1] * rs, b0 = acc[ai][1][m][0] * rs, b1 = acc[ai][1][m][1] * rs;
;                 if (pn == 0) {
;                     float s = 0.f;
; #pragma unroll
;                     for (int e = 0; e < 4; ++e) s += a0[e] * a0[e] + a1[e] * a1[e] + b0[e] * b0[e] + b1[e] * b1[e];
;                     s += __shfl_xor(s, 16); s += __shfl_xor(s, 32);
;                     if (fq == 0) ssq_q[row * 4 + wc] = s;
;                     *(u32x4*)(LAT + (size_t)row * 512 + cw) = pack8(a0, a1); *(u32x4*)(LAT + (size_t)row * 512 + 128 + cw) = pack8(b0, b1);
;                 } else if (pn == 1) {
;                     float s = 0.f;
; #pragma unroll
;                     for (int e = 0; e < 4; ++e) s += a0[e] * a0[e] + a1[e] * a1[e];
;                     s += __shfl_xor(s, 16); s += __shfl_xor(s, 32);
;                     if (fq == 0) ssq_kv[row * 4 + wc] = s;
;                     *(u32x4*)(LAT + (size_t)row * 512 + 256 + cw) = pack8(a0, a1);
.LBB0_703:
	s_waitcnt lgkmcnt(0)
	v_pk_mul_f32 v[64:65], v[64:65], v[74:75] op_sel_hi:[1,0]
	v_pk_mul_f32 v[62:63], v[62:63], v[74:75] op_sel_hi:[1,0]
	v_pk_mul_f32 v[60:61], v[60:61], v[74:75] op_sel_hi:[1,0]
	v_pk_mul_f32 v[72:73], v[58:59], v[74:75] op_sel_hi:[1,0]
	v_pk_mul_f32 v[58:59], v[56:57], v[74:75] op_sel_hi:[1,0]
	v_pk_mul_f32 v[68:69], v[54:55], v[74:75] op_sel_hi:[1,0]
	v_pk_mul_f32 v[70:71], v[52:53], v[74:75] op_sel_hi:[1,0]
	v_pk_mul_f32 v[74:75], v[50:51], v[74:75] op_sel_hi:[1,0]
	s_mov_b64 s[28:29], -1
	s_mov_b64 s[20:21], 0
	s_cmp_lt_i32 s82, 1
	s_mov_b64 s[24:25], 0
	s_cbranch_scc1 .LBB0_731
	s_cmp_eq_u32 s82, 1
	s_mov_b64 s[24:25], -1
	s_cbranch_scc0 .LBB0_710
	v_mul_f32_e32 v50, v72, v72
	v_mul_f32_e32 v51, v73, v73
	v_fmac_f32_e32 v50, v62, v62
	v_fmac_f32_e32 v51, v63, v63
	v_add_f32_e32 v50, v50, v51
	v_mul_f32_e32 v51, v60, v60
	v_fmac_f32_e32 v51, v64, v64
	v_add_f32_e32 v50, v51, v50
	v_mul_f32_e32 v51, v61, v61
	v_fmac_f32_e32 v51, v65, v65
	v_and_b32_e32 v52, 64, v217
	v_add_f32_e32 v50, v51, v50
	v_add_u32_e32 v52, 64, v52
	s_nop 1
	v_mov_b32_e32 v51, v50
	s_nop 1
	v_permlane16_swap_b32_e32 v51, v50
	s_waitcnt lgkmcnt(0)
	v_add_f32_e32 v50, v50, v51
	s_nop 1
	v_mov_b32_e32 v51, v50
	s_nop 1
	v_permlane32_swap_b32_e32 v51, v50
	s_and_saveexec_b64 s[24:25], s[42:43]
	s_cbranch_execz .LBB0_707
	s_waitcnt lgkmcnt(0)
	v_add_f32_e32 v52, v50, v51
	v_lshl_or_b32 v50, v66, 2, s76
	v_ashrrev_i32_e32 v51, 31, v50
	v_lshl_add_u64 v[50:51], v[50:51], 2, s[62:63]
	flat_store_dword v[50:51], v52

; __device__ __forceinline__ u32x4 pack8(f32x4 a, f32x4 b) { u32x4 w; w.x = pk2(a[0], a[1]); w.y = pk2(a[2], a[3]); w.z = pk2(b[0], b[1]); w.w = pk2(b[2], b[3]); return w; }
;     __device__ __forceinline__ void operator()(const Acc& acc, const Unit& u, int wr, int wc, int fr, int fq, const RsCtx& rc) const {
;     ...
;                 if (pn == 0) {
;                     float s = 0.f;
; #pragma unroll
;                     for (int e = 0; e < 4; ++e) s += a0[e] * a0[e] + a1[e] * a1[e] + b0[e] * b0[e] + b1[e] * b1[e];
;                     s += __shfl_xor(s, 16); s += __shfl_xor(s, 32);
;                     if (fq == 0) ssq_q[row * 4 + wc] = s;
;                     *(u32x4*)(LAT + (size_t)row * 512 + cw) = pack8(a0, a1); *(u32x4*)(LAT + (size_t)row * 512 + 128 + cw) = pack8(b0, b1);
.LBB0_734:
	s_nop 0
	v_mul_f32_e32 v50, v72, v72
	v_mul_f32_e32 v51, v73, v73
	v_fmac_f32_e32 v50, v62, v62
	v_fmac_f32_e32 v51, v63, v63
	v_fmac_f32_e32 v50, v68, v68
	v_fmac_f32_e32 v51, v69, v69
	v_fmac_f32_e32 v50, v74, v74
	v_fmac_f32_e32 v51, v75, v75
	v_add_f32_e32 v50, v50, v51
	v_mul_f32_e32 v51, v60, v60
	v_fmac_f32_e32 v51, v64, v64
	v_fmac_f32_e32 v51, v58, v58
	v_fmac_f32_e32 v51, v70, v70
	v_add_f32_e32 v50, v51, v50
	v_mul_f32_e32 v51, v61, v61
	v_fmac_f32_e32 v51, v65, v65
	v_fmac_f32_e32 v51, v59, v59
	v_fmac_f32_e32 v51, v71, v71
	v_and_b32_e32 v52, 64, v217
	v_add_f32_e32 v50, v51, v50
	v_add_u32_e32 v52, 64, v52
	s_nop 1
	v_mov_b32_e32 v51, v50
	s_nop 1
	v_permlane16_swap_b32_e32 v51, v50
	s_waitcnt lgkmcnt(0)
	v_add_f32_e32 v50, v50, v51
	s_nop 1
	v_mov_b32_e32 v51, v50
	s_nop 1
	v_permlane32_swap_b32_e32 v51, v50
	s_and_saveexec_b64 s[20:21], s[42:43]
	s_cbranch_execz .LBB0_736
	s_waitcnt lgkmcnt(0)
	v_add_f32_e32 v52, v50, v51
	v_lshl_or_b32 v50, v66, 2, s76
	v_readlane_b32 s36, v254, 54
	v_ashrrev_i32_e32 v51, 31, v50
	v_readlane_b32 s37, v254, 55
	v_readlane_b32 s38, v254, 56
	v_readlane_b32 s39, v254, 57
	v_readlane_b32 s36, v254, 44
	v_readlane_b32 s37, v254, 45
	v_lshl_add_u64 v[50:51], v[50:51], 2, s[38:39]
	v_readlane_b32 s38, v254, 48
	v_readlane_b32 s39, v254, 49
	flat_store_dword v[50:51], v52

; __device__ __forceinline__ u32x4 pack8(f32x4 a, f32x4 b) { u32x4 w; w.x = pk2(a[0], a[1]); w.y = pk2(a[2], a[3]); w.z = pk2(b[0], b[1]); w.w = pk2(b[2], b[3]); return w; }
;     __device__ __forceinline__ void operator()(const Acc& acc, const Unit& u, int wr, int wc, int fr, int fq, const RsCtx& rc) const {
;     ...
;             for (int m = 0; m < 4; ++m) { const int row = EPI_ROW(u, ai, wr, m, fr);
;                 const float rs = rc.get(u.pm, ai * 128 + wr * 64 + m * 16 + fr, row);
;                 f32x4 a0 = acc[ai][0][m][0] * rs, a1 = acc[ai][0][m][1] * rs, b0 = acc[ai][1][m][0] * rs, b1 = acc[ai][1][m][1] * rs;
;                 if (pn == 0) {
;                     float s = 0.f;
; #pragma unroll
;                     for (int e = 0; e < 4; ++e) s += a0[e] * a0[e] + a1[e] * a1[e] + b0[e] * b0[e] + b1[e] * b1[e];
;                     s += __shfl_xor(s, 16); s += __shfl_xor(s, 32);
;                     if (fq == 0) ssq_q[row * 4 + wc] = s;
;                     *(u32x4*)(LAT + (size_t)row * 512 + cw) = pack8(a0, a1); *(u32x4*)(LAT + (size_t)row * 512 + 128 + cw) = pack8(b0, b1);
;                 } else if (pn == 1) {
;                     float s = 0.f;
; #pragma unroll
;                     for (int e = 0; e < 4; ++e) s += a0[e] * a0[e] + a1[e] * a1[e];
;                     s += __shfl_xor(s, 16); s += __shfl_xor(s, 32);
;                     if (fq == 0) ssq_kv[row * 4 + wc] = s;
;                     *(u32x4*)(LAT + (size_t)row * 512 + 256 + cw) = pack8(a0, a1);
.LBB0_739:
	s_waitcnt lgkmcnt(0)
	v_pk_mul_f32 v[48:49], v[48:49], v[58:59] op_sel_hi:[1,0]
	v_pk_mul_f32 v[46:47], v[46:47], v[58:59] op_sel_hi:[1,0]
	v_pk_mul_f32 v[44:45], v[44:45], v[58:59] op_sel_hi:[1,0]
	v_pk_mul_f32 v[56:57], v[42:43], v[58:59] op_sel_hi:[1,0]
	v_pk_mul_f32 v[42:43], v[40:41], v[58:59] op_sel_hi:[1,0]
	v_pk_mul_f32 v[52:53], v[38:39], v[58:59] op_sel_hi:[1,0]
	v_pk_mul_f32 v[54:55], v[36:37], v[58:59] op_sel_hi:[1,0]
	v_pk_mul_f32 v[58:59], v[34:35], v[58:59] op_sel_hi:[1,0]
	s_mov_b64 s[28:29], -1
	s_mov_b64 s[20:21], 0
	s_cmp_lt_i32 s82, 1
	s_mov_b64 s[24:25], 0
	s_cbranch_scc1 .LBB0_767
	s_cmp_eq_u32 s82, 1
	s_mov_b64 s[24:25], -1
	s_cbranch_scc0 .LBB0_746
	v_mul_f32_e32 v34, v56, v56
	v_mul_f32_e32 v35, v57, v57
	v_fmac_f32_e32 v34, v46, v46
	v_fmac_f32_e32 v35, v47, v47
	v_add_f32_e32 v34, v34, v35
	v_mul_f32_e32 v35, v44, v44
	v_fmac_f32_e32 v35, v48, v48
	v_add_f32_e32 v34, v35, v34
	v_mul_f32_e32 v35, v45, v45
	v_fmac_f32_e32 v35, v49, v49
	v_and_b32_e32 v36, 64, v217
	v_add_f32_e32 v34, v35, v34
	v_add_u32_e32 v36, 64, v36
	s_nop 1
	v_mov_b32_e32 v35, v34
	s_nop 1
	v_permlane16_swap_b32_e32 v35, v34
	s_waitcnt lgkmcnt(0)
	v_add_f32_e32 v34, v34, v35
	s_nop 1
	v_mov_b32_e32 v35, v34
	s_nop 1
	v_permlane32_swap_b32_e32 v35, v34
	s_and_saveexec_b64 s[24:25], s[42:43]
	s_cbranch_execz .LBB0_743
	s_waitcnt lgkmcnt(0)
	v_add_f32_e32 v36, v34, v35
	v_lshl_or_b32 v34, v50, 2, s76
	v_ashrrev_i32_e32 v35, 31, v34
	v_lshl_add_u64 v[34:35], v[34:35], 2, s[62:63]
	flat_store_dword v[34:35], v36

; __device__ __forceinline__ u32x4 pack8(f32x4 a, f32x4 b) { u32x4 w; w.x = pk2(a[0], a[1]); w.y = pk2(a[2], a[3]); w.z = pk2(b[0], b[1]); w.w = pk2(b[2], b[3]); return w; }
;     __device__ __forceinline__ void operator()(const Acc& acc, const Unit& u, int wr, int wc, int fr, int fq, const RsCtx& rc) const {
;     ...
;                 if (pn == 0) {
;                     float s = 0.f;
; #pragma unroll
;                     for (int e = 0; e < 4; ++e) s += a0[e] * a0[e] + a1[e] * a1[e] + b0[e] * b0[e] + b1[e] * b1[e];
;                     s += __shfl_xor(s, 16); s += __shfl_xor(s, 32);
;                     if (fq == 0) ssq_q[row * 4 + wc] = s;
;                     *(u32x4*)(LAT + (size_t)row * 512 + cw) = pack8(a0, a1); *(u32x4*)(LAT + (size_t)row * 512 + 128 + cw) = pack8(b0, b1);
.LBB0_770:
	s_nop 0
	v_mul_f32_e32 v34, v56, v56
	v_mul_f32_e32 v35, v57, v57
	v_fmac_f32_e32 v34, v46, v46
	v_fmac_f32_e32 v35, v47, v47
	v_fmac_f32_e32 v34, v52, v52
	v_fmac_f32_e32 v35, v53, v53
	v_fmac_f32_e32 v34, v58, v58
	v_fmac_f32_e32 v35, v59, v59
	v_add_f32_e32 v34, v34, v35
	v_mul_f32_e32 v35, v44, v44
	v_fmac_f32_e32 v35, v48, v48
	v_fmac_f32_e32 v35, v42, v42
	v_fmac_f32_e32 v35, v54, v54
	v_add_f32_e32 v34, v35, v34
	v_mul_f32_e32 v35, v45, v45
	v_fmac_f32_e32 v35, v49, v49
	v_fmac_f32_e32 v35, v43, v43
	v_fmac_f32_e32 v35, v55, v55
	v_and_b32_e32 v36, 64, v217
	v_add_f32_e32 v34, v35, v34
	v_add_u32_e32 v36, 64, v36
	s_nop 1
	v_mov_b32_e32 v35, v34
	s_nop 1
	v_permlane16_swap_b32_e32 v35, v34
	s_waitcnt lgkmcnt(0)
	v_add_f32_e32 v34, v34, v35
	s_nop 1
	v_mov_b32_e32 v35, v34
	s_nop 1
	v_permlane32_swap_b32_e32 v35, v34
	s_and_saveexec_b64 s[20:21], s[42:43]
	s_cbranch_execz .LBB0_772
	s_waitcnt lgkmcnt(0)
	v_add_f32_e32 v36, v34, v35
	v_lshl_or_b32 v34, v50, 2, s76
	v_readlane_b32 s36, v254, 54
	v_ashrrev_i32_e32 v35, 31, v34
	v_readlane_b32 s37, v254, 55
	v_readlane_b32 s38, v254, 56
	v_readlane_b32 s39, v254, 57
	v_readlane_b32 s36, v254, 44
	v_readlane_b32 s37, v254, 45
	v_lshl_add_u64 v[34:35], v[34:35], 2, s[38:39]
	v_readlane_b32 s38, v254, 48
	v_readlane_b32 s39, v254, 49
	flat_store_dword v[34:35], v36

; __device__ __forceinline__ u32x4 pack8(f32x4 a, f32x4 b) { u32x4 w; w.x = pk2(a[0], a[1]); w.y = pk2(a[2], a[3]); w.z = pk2(b[0], b[1]); w.w = pk2(b[2], b[3]); return w; }
;     __device__ __forceinline__ void operator()(const Acc& acc, const Unit& u, int wr, int wc, int fr, int fq, const RsCtx& rc) const {
;     ...
;             for (int m = 0; m < 4; ++m) { const int row = EPI_ROW(u, ai, wr, m, fr);
;                 const float rs = rc.get(u.pm, ai * 128 + wr * 64 + m * 16 + fr, row);
;                 f32x4 a0 = acc[ai][0][m][0] * rs, a1 = acc[ai][0][m][1] * rs, b0 = acc[ai][1][m][0] * rs, b1 = acc[ai][1][m][1] * rs;
;                 if (pn == 0) {
;                     float s = 0.f;
; #pragma unroll
;                     for (int e = 0; e < 4; ++e) s += a0[e] * a0[e] + a1[e] * a1[e] + b0[e] * b0[e] + b1[e] * b1[e];
;                     s += __shfl_xor(s, 16); s += __shfl_xor(s, 32);
;                     if (fq == 0) ssq_q[row * 4 + wc] = s;
;                     *(u32x4*)(LAT + (size_t)row * 512 + cw) = pack8(a0, a1); *(u32x4*)(LAT + (size_t)row * 512 + 128 + cw) = pack8(b0, b1);
;                 } else if (pn == 1) {
;                     float s = 0.f;
; #pragma unroll
;                     for (int e = 0; e < 4; ++e) s += a0[e] * a0[e] + a1[e] * a1[e];
;                     s += __shfl_xor(s, 16); s += __shfl_xor(s, 32);
;                     if (fq == 0) ssq_kv[row * 4 + wc] = s;
;                     *(u32x4*)(LAT + (size_t)row * 512 + 256 + cw) = pack8(a0, a1);
.LBB0_775:
	s_waitcnt lgkmcnt(0)
	v_pk_mul_f32 v[32:33], v[32:33], v[42:43] op_sel_hi:[1,0]
	v_pk_mul_f32 v[30:31], v[30:31], v[42:43] op_sel_hi:[1,0]
	v_pk_mul_f32 v[28:29], v[28:29], v[42:43] op_sel_hi:[1,0]
	v_pk_mul_f32 v[40:41], v[26:27], v[42:43] op_sel_hi:[1,0]
	v_pk_mul_f32 v[26:27], v[24:25], v[42:43] op_sel_hi:[1,0]
	v_pk_mul_f32 v[36:37], v[22:23], v[42:43] op_sel_hi:[1,0]
	v_pk_mul_f32 v[38:39], v[20:21], v[42:43] op_sel_hi:[1,0]
	v_pk_mul_f32 v[42:43], v[18:19], v[42:43] op_sel_hi:[1,0]
	s_mov_b64 s[28:29], -1
	s_mov_b64 s[20:21], 0
	s_cmp_lt_i32 s82, 1
	s_mov_b64 s[24:25], 0
	s_cbranch_scc1 .LBB0_803
	s_cmp_eq_u32 s82, 1
	s_mov_b64 s[24:25], -1
	s_cbranch_scc0 .LBB0_782
	v_mul_f32_e32 v18, v40, v40
	v_mul_f32_e32 v19, v41, v41
	v_fmac_f32_e32 v18, v30, v30
	v_fmac_f32_e32 v19, v31, v31
	v_add_f32_e32 v18, v18, v19
	v_mul_f32_e32 v19, v28, v28
	v_fmac_f32_e32 v19, v32, v32
	v_add_f32_e32 v18, v19, v18
	v_mul_f32_e32 v19, v29, v29
	v_fmac_f32_e32 v19, v33, v33
	v_and_b32_e32 v20, 64, v217
	v_add_f32_e32 v18, v19, v18
	v_add_u32_e32 v20, 64, v20
	s_nop 1
	v_mov_b32_e32 v19, v18
	s_nop 1
	v_permlane16_swap_b32_e32 v19, v18
	s_waitcnt lgkmcnt(0)
	v_add_f32_e32 v18, v18, v19
	s_nop 1
	v_mov_b32_e32 v19, v18
	s_nop 1
	v_permlane32_swap_b32_e32 v19, v18
	s_and_saveexec_b64 s[24:25], s[42:43]
	s_cbranch_execz .LBB0_779
	s_waitcnt lgkmcnt(0)
	v_add_f32_e32 v20, v18, v19
	v_lshl_or_b32 v18, v34, 2, s76
	v_ashrrev_i32_e32 v19, 31, v18
	v_lshl_add_u64 v[18:19], v[18:19], 2, s[62:63]
	flat_store_dword v[18:19], v20

; __device__ __forceinline__ u32x4 pack8(f32x4 a, f32x4 b) { u32x4 w; w.x = pk2(a[0], a[1]); w.y = pk2(a[2], a[3]); w.z = pk2(b[0], b[1]); w.w = pk2(b[2], b[3]); return w; }
;     __device__ __forceinline__ void operator()(const Acc& acc, const Unit& u, int wr, int wc, int fr, int fq, const RsCtx& rc) const {
;     ...
;                 if (pn == 0) {
;                     float s = 0.f;
; #pragma unroll
;                     for (int e = 0; e < 4; ++e) s += a0[e] * a0[e] + a1[e] * a1[e] + b0[e] * b0[e] + b1[e] * b1[e];
;                     s += __shfl_xor(s, 16); s += __shfl_xor(s, 32);
;                     if (fq == 0) ssq_q[row * 4 + wc] = s;
;                     *(u32x4*)(LAT + (size_t)row * 512 + cw) = pack8(a0, a1); *(u32x4*)(LAT + (size_t)row * 512 + 128 + cw) = pack8(b0, b1);
.LBB0_806:
	s_nop 0
	v_mul_f32_e32 v18, v40, v40
	v_mul_f32_e32 v19, v41, v41
	v_fmac_f32_e32 v18, v30, v30
	v_fmac_f32_e32 v19, v31, v31
	v_fmac_f32_e32 v18, v36, v36
	v_fmac_f32_e32 v19, v37, v37
	v_fmac_f32_e32 v18, v42, v42
	v_fmac_f32_e32 v19, v43, v43
	v_add_f32_e32 v18, v18, v19
	v_mul_f32_e32 v19, v28, v28
	v_fmac_f32_e32 v19, v32, v32
	v_fmac_f32_e32 v19, v26, v26
	v_fmac_f32_e32 v19, v38, v38
	v_add_f32_e32 v18, v19, v18
	v_mul_f32_e32 v19, v29, v29
	v_fmac_f32_e32 v19, v33, v33
	v_fmac_f32_e32 v19, v27, v27
	v_fmac_f32_e32 v19, v39, v39
	v_and_b32_e32 v20, 64, v217
	v_add_f32_e32 v18, v19, v18
	v_add_u32_e32 v20, 64, v20
	s_nop 1
	v_mov_b32_e32 v19, v18
	s_nop 1
	v_permlane16_swap_b32_e32 v19, v18
	s_waitcnt lgkmcnt(0)
	v_add_f32_e32 v18, v18, v19
	s_nop 1
	v_mov_b32_e32 v19, v18
	s_nop 1
	v_permlane32_swap_b32_e32 v19, v18
	s_and_saveexec_b64 s[20:21], s[42:43]
	s_cbranch_execz .LBB0_808
	s_waitcnt lgkmcnt(0)
	v_add_f32_e32 v20, v18, v19
	v_lshl_or_b32 v18, v34, 2, s76
	v_readlane_b32 s36, v254, 54
	v_ashrrev_i32_e32 v19, 31, v18
	v_readlane_b32 s37, v254, 55
	v_readlane_b32 s38, v254, 56
	v_readlane_b32 s39, v254, 57
	v_readlane_b32 s36, v254, 44
	v_readlane_b32 s37, v254, 45
	v_lshl_add_u64 v[18:19], v[18:19], 2, s[38:39]
	v_readlane_b32 s38, v254, 48
	v_readlane_b32 s39, v254, 49
	flat_store_dword v[18:19], v20

; __device__ __forceinline__ u32x4 pack8(f32x4 a, f32x4 b) { u32x4 w; w.x = pk2(a[0], a[1]); w.y = pk2(a[2], a[3]); w.z = pk2(b[0], b[1]); w.w = pk2(b[2], b[3]); return w; }
;     __device__ __forceinline__ void operator()(const Acc& acc, const Unit& u, int wr, int wc, int fr, int fq, const RsCtx& rc) const {
;     ...
;             for (int m = 0; m < 4; ++m) { const int row = EPI_ROW(u, ai, wr, m, fr);
;                 const float rs = rc.get(u.pm, ai * 128 + wr * 64 + m * 16 + fr, row);
;                 f32x4 a0 = acc[ai][0][m][0] * rs, a1 = acc[ai][0][m][1] * rs, b0 = acc[ai][1][m][0] * rs, b1 = acc[ai][1][m][1] * rs;
;                 if (pn == 0) {
;                     float s = 0.f;
; #pragma unroll
;                     for (int e = 0; e < 4; ++e) s += a0[e] * a0[e] + a1[e] * a1[e] + b0[e] * b0[e] + b1[e] * b1[e];
;                     s += __shfl_xor(s, 16); s += __shfl_xor(s, 32);
;                     if (fq == 0) ssq_q[row * 4 + wc] = s;
;                     *(u32x4*)(LAT + (size_t)row * 512 + cw) = pack8(a0, a1); *(u32x4*)(LAT + (size_t)row * 512 + 128 + cw) = pack8(b0, b1);
;                 } else if (pn == 1) {
;                     float s = 0.f;
; #pragma unroll
;                     for (int e = 0; e < 4; ++e) s += a0[e] * a0[e] + a1[e] * a1[e];
;                     s += __shfl_xor(s, 16); s += __shfl_xor(s, 32);
;                     if (fq == 0) ssq_kv[row * 4 + wc] = s;
;                     *(u32x4*)(LAT + (size_t)row * 512 + 256 + cw) = pack8(a0, a1);
.LBB0_811:
	s_waitcnt lgkmcnt(0)
	v_pk_mul_f32 v[16:17], v[16:17], v[26:27] op_sel_hi:[1,0]
	v_pk_mul_f32 v[14:15], v[14:15], v[26:27] op_sel_hi:[1,0]
	v_pk_mul_f32 v[12:13], v[12:13], v[26:27] op_sel_hi:[1,0]
	v_pk_mul_f32 v[24:25], v[10:11], v[26:27] op_sel_hi:[1,0]
	v_pk_mul_f32 v[10:11], v[8:9], v[26:27] op_sel_hi:[1,0]
	v_pk_mul_f32 v[20:21], v[6:7], v[26:27] op_sel_hi:[1,0]
	v_pk_mul_f32 v[22:23], v[4:5], v[26:27] op_sel_hi:[1,0]
	v_pk_mul_f32 v[26:27], v[2:3], v[26:27] op_sel_hi:[1,0]
	s_mov_b64 s[24:25], -1
	s_mov_b64 s[6:7], 0
	s_cmp_lt_i32 s82, 1
	s_mov_b64 s[20:21], 0
	s_cbranch_scc1 .LBB0_833
	s_cmp_eq_u32 s82, 1
	s_mov_b64 s[20:21], -1
	s_cbranch_scc0 .LBB0_818
	v_mul_f32_e32 v2, v24, v24
	v_mul_f32_e32 v3, v25, v25
	v_fmac_f32_e32 v2, v14, v14
	v_fmac_f32_e32 v3, v15, v15
	v_add_f32_e32 v2, v2, v3
	v_mul_f32_e32 v3, v12, v12
	v_fmac_f32_e32 v3, v16, v16
	v_add_f32_e32 v2, v3, v2
	v_mul_f32_e32 v3, v13, v13
	v_fmac_f32_e32 v3, v17, v17
	v_and_b32_e32 v4, 64, v217
	v_add_f32_e32 v2, v3, v2
	v_add_u32_e32 v4, 64, v4
	s_nop 1
	v_mov_b32_e32 v3, v2
	s_nop 1
	v_permlane16_swap_b32_e32 v3, v2
	s_waitcnt lgkmcnt(0)
	v_add_f32_e32 v2, v2, v3
	s_nop 1
	v_mov_b32_e32 v3, v2
	s_nop 1
	v_permlane32_swap_b32_e32 v3, v2
	s_and_saveexec_b64 s[20:21], s[42:43]
	s_cbranch_execz .LBB0_815
	s_waitcnt lgkmcnt(0)
	v_add_f32_e32 v4, v2, v3
	v_lshl_or_b32 v2, v18, 2, s76
	v_ashrrev_i32_e32 v3, 31, v2
	v_lshl_add_u64 v[2:3], v[2:3], 2, s[62:63]
	flat_store_dword v[2:3], v4

; __device__ __forceinline__ u32x4 pack8(f32x4 a, f32x4 b) { u32x4 w; w.x = pk2(a[0], a[1]); w.y = pk2(a[2], a[3]); w.z = pk2(b[0], b[1]); w.w = pk2(b[2], b[3]); return w; }
;     __device__ __forceinline__ void operator()(const Acc& acc, const Unit& u, int wr, int wc, int fr, int fq, const RsCtx& rc) const {
;     ...
;                 if (pn == 0) {
;                     float s = 0.f;
; #pragma unroll
;                     for (int e = 0; e < 4; ++e) s += a0[e] * a0[e] + a1[e] * a1[e] + b0[e] * b0[e] + b1[e] * b1[e];
;                     s += __shfl_xor(s, 16); s += __shfl_xor(s, 32);
;                     if (fq == 0) ssq_q[row * 4 + wc] = s;
;                     *(u32x4*)(LAT + (size_t)row * 512 + cw) = pack8(a0, a1); *(u32x4*)(LAT + (size_t)row * 512 + 128 + cw) = pack8(b0, b1);
.LBB0_836:
	v_mul_f32_e32 v0, v24, v24
	v_mul_f32_e32 v2, v25, v25
	v_fmac_f32_e32 v0, v14, v14
	v_fmac_f32_e32 v2, v15, v15
	v_fmac_f32_e32 v0, v20, v20
	v_fmac_f32_e32 v2, v21, v21
	v_fmac_f32_e32 v0, v26, v26
	v_fmac_f32_e32 v2, v27, v27
	v_add_f32_e32 v0, v0, v2
	v_mul_f32_e32 v2, v12, v12
	v_fmac_f32_e32 v2, v16, v16
	v_fmac_f32_e32 v2, v10, v10
	v_fmac_f32_e32 v2, v22, v22
	v_add_f32_e32 v0, v2, v0
	v_mul_f32_e32 v2, v13, v13
	v_fmac_f32_e32 v2, v17, v17
	v_fmac_f32_e32 v2, v11, v11
	v_fmac_f32_e32 v2, v23, v23
	v_and_b32_e32 v3, 64, v217
	v_add_f32_e32 v0, v2, v0
	v_add_u32_e32 v3, 64, v3
	s_nop 1
	v_mov_b32_e32 v2, v0
	s_nop 1
	v_permlane16_swap_b32_e32 v2, v0
	s_waitcnt lgkmcnt(0)
	v_add_f32_e32 v0, v0, v2
	s_nop 1
	v_mov_b32_e32 v2, v0
	s_nop 1
	v_permlane32_swap_b32_e32 v2, v0
	s_and_saveexec_b64 s[4:5], s[42:43]
	s_cbranch_execz .LBB0_838
	s_waitcnt lgkmcnt(0)
	v_add_f32_e32 v0, v0, v2
	v_lshl_or_b32 v2, v18, 2, s76
	v_readlane_b32 s12, v254, 54
	v_ashrrev_i32_e32 v3, 31, v2
	v_readlane_b32 s14, v254, 56
	v_readlane_b32 s15, v254, 57
	v_readlane_b32 s13, v254, 55
	s_nop 0
	v_lshl_add_u64 v[2:3], v[2:3], 2, s[14:15]
	flat_store_dword v[2:3], v0

; __device__ __forceinline__ u32x4 pack8(f32x4 a, f32x4 b) { u32x4 w; w.x = pk2(a[0], a[1]); w.y = pk2(a[2], a[3]); w.z = pk2(b[0], b[1]); w.w = pk2(b[2], b[3]); return w; }
; __device__ __forceinline__ void unpack8(u32x4 w, f32x4& a, f32x4& b) { a = (f32x4){bflo(w.x), bfhi(w.x), bflo(w.y), bfhi(w.y)}; b = (f32x4){bflo(w.z), bfhi(w.z), bflo(w.w), bfhi(w.w)}; }
;     __device__ __forceinline__ void operator()(const Acc& acc, const Unit& u, int wr, int wc, int fr, int fq, const RsCtx& rc) const {
;     ...
;             for (int m = 0; m < 4; ++m) { const int row = EPI_ROW(u, ai, wr, m, fr); float s = 0.f;
; #pragma unroll
;                 for (int bj = 0; bj < 2; ++bj) { const size_t off = (size_t)row * DM + u.pn * 256 + bj * 128 + wc * 32 + 8 * fq;
;                     f32x4 x0, x1; unpack8(*(const u32x4*)(XB + off), x0, x1);
;                     x0 = x0 + acc[ai][bj][m][0] * alpha; x1 = x1 + acc[ai][bj][m][1] * alpha;
;                     *(u32x4*)(XB + off) = pack8(x0, x1);
; #pragma unroll
;                     for (int e = 0; e < 4; ++e) s += x0[e] * x0[e] + x1[e] * x1[e]; }
;                 s += __shfl_xor(s, 16); s += __shfl_xor(s, 32);
;                 if (fq == 0) ssq_x[(size_t)row * 16 + u.pn * 4 + wc] = s;
.LBB0_1104:
	v_and_b32_e32 v149, 64, v217
	v_xor_b32_e32 v0, 16, v217
	v_add_u32_e32 v149, 64, v149
	v_cmp_lt_i32_e32 vcc, v0, v149
	v_lshl_add_u32 v148, s37, 8, v141
	s_lshl_b32 s50, s36, 8
	v_cndmask_b32_e32 v0, v217, v0, vcc
	v_lshlrev_b32_e32 v155, 2, v0
	v_xor_b32_e32 v0, 32, v217
	v_cmp_lt_i32_e32 vcc, v0, v149
	s_lshl_b32 s48, s36, 2
	v_ashrrev_i32_e32 v149, 31, v148
	v_readlane_b32 s36, v254, 44
	v_lshlrev_b64 v[150:151], 11, v[148:149]
	v_readlane_b32 s37, v254, 45
	s_ashr_i32 s51, s50, 31
	v_cndmask_b32_e32 v0, v217, v0, vcc
	v_lshl_add_u64 v[150:151], s[36:37], 0, v[150:151]
	v_lshl_add_u64 v[150:151], s[50:51], 1, v[150:151]
	s_lshl_b32 s92, s55, 1
	v_lshlrev_b32_e32 v154, 2, v0
	v_lshl_add_u64 v[150:151], v[150:151], 0, s[92:93]
	v_lshlrev_b32_e32 v0, 1, v140
	v_lshl_add_u64 v[150:151], v[150:151], 0, v[0:1]
	v_lshl_add_u32 v210, v148, 11, v0
	s_lshl_b64 s[28:29], s[50:51], 1
	s_add_u32 s28, s28, s36
	s_addc_u32 s29, s29, s37
	s_add_u32 s28, s28, s92
	s_addc_u32 s29, s29, s93
	global_load_dwordx4 v[156:159], v210, s[28:29]
	global_load_dwordx4 v[164:167], v210, s[28:29] offset:256
	s_add_u32 s28, s28, 0x8000
	s_addc_u32 s29, s29, 0
	global_load_dwordx4 v[168:171], v210, s[28:29]
	global_load_dwordx4 v[172:175], v210, s[28:29] offset:256
	s_add_u32 s28, s28, 0x8000
	s_addc_u32 s29, s29, 0
	global_load_dwordx4 v[176:179], v210, s[28:29]
	global_load_dwordx4 v[180:183], v210, s[28:29] offset:256
	s_add_u32 s28, s28, 0x8000
	s_addc_u32 s29, s29, 0
	global_load_dwordx4 v[184:187], v210, s[28:29]
	global_load_dwordx4 v[188:191], v210, s[28:29] offset:256
	s_add_u32 s28, s28, 0x28000
	s_addc_u32 s29, s29, 0
	global_load_dwordx4 v[192:195], v210, s[28:29]
	global_load_dwordx4 v[206:209], v210, s[28:29] offset:256
	s_add_u32 s28, s28, 0x8000
	s_addc_u32 s29, s29, 0
	global_load_dwordx4 v[218:221], v210, s[28:29]
	global_load_dwordx4 v[232:235], v210, s[28:29] offset:256
	s_add_u32 s28, s28, 0x8000
	s_addc_u32 s29, s29, 0
	global_load_dwordx4 v[236:239], v210, s[28:29]
	global_load_dwordx4 v[240:243], v210, s[28:29] offset:256
	s_add_u32 s28, s28, 0x8000
	s_addc_u32 s29, s29, 0
	global_load_dwordx4 v[244:247], v210, s[28:29]
	global_load_dwordx4 v[248:251], v210, s[28:29] offset:256
	s_ashr_i32 s49, s48, 31
	s_waitcnt vmcnt(0) lgkmcnt(0)
	v_lshlrev_b32_e32 v160, 16, v156
	v_and_b32_e32 v161, 0xffff0000, v156
	v_lshlrev_b32_e32 v156, 16, v157
	v_and_b32_e32 v157, 0xffff0000, v157
	v_lshlrev_b32_e32 v162, 16, v158
	v_and_b32_e32 v163, 0xffff0000, v158
	v_lshlrev_b32_e32 v158, 16, v159
	v_and_b32_e32 v159, 0xffff0000, v159
	v_pk_fma_f32 v[156:157], v[142:143], v[124:125], v[156:157]
	v_pk_fma_f32 v[160:161], v[130:131], v[122:123], v[160:161]
	v_pk_fma_f32 v[128:129], v[142:143], v[128:129], v[158:159]
	v_pk_fma_f32 v[126:127], v[130:131], v[126:127], v[162:163]
	v_cvt_pk_bf16_f32 v122, v160, v161
	v_cvt_pk_bf16_f32 v123, v156, v157
	v_cvt_pk_bf16_f32 v124, v126, v127
	v_cvt_pk_bf16_f32 v125, v128, v129
	flat_store_dwordx4 v[150:151], v[122:125]
	s_nop 1
	v_mul_f32_e32 v122, v126, v126
	v_mul_f32_e32 v123, v127, v127
	v_fmac_f32_e32 v122, v160, v160
	v_fmac_f32_e32 v123, v161, v161
	v_add_f32_e32 v122, v122, v123
	v_mul_f32_e32 v123, v128, v128
	v_fmac_f32_e32 v123, v156, v156
	v_add_f32_e32 v122, v123, v122
	v_mul_f32_e32 v123, v129, v129
	v_fmac_f32_e32 v123, v157, v157
	v_add_f32_e32 v156, v123, v122
	v_mov_b64_e32 v[122:123], v[164:165]
	v_mov_b64_e32 v[124:125], v[166:167]
	s_waitcnt lgkmcnt(0)
	v_lshlrev_b32_e32 v126, 16, v122
	v_and_b32_e32 v127, 0xffff0000, v122
	v_lshlrev_b32_e32 v122, 16, v123
	v_and_b32_e32 v123, 0xffff0000, v123
	v_lshlrev_b32_e32 v128, 16, v124
	v_and_b32_e32 v129, 0xffff0000, v124
	v_lshlrev_b32_e32 v124, 16, v125
	v_and_b32_e32 v125, 0xffff0000, v125
	v_pk_fma_f32 v[120:121], v[142:143], v[120:121], v[122:123]
	v_pk_fma_f32 v[118:119], v[130:131], v[118:119], v[126:127]
	v_pk_fma_f32 v[122:123], v[142:143], v[116:117], v[124:125]
	v_pk_fma_f32 v[124:125], v[130:131], v[114:115], v[128:129]
	v_cvt_pk_bf16_f32 v114, v118, v119
	v_cvt_pk_bf16_f32 v115, v120, v121
	v_cvt_pk_bf16_f32 v116, v124, v125
	v_cvt_pk_bf16_f32 v117, v122, v123
	flat_store_dwordx4 v[150:151], v[114:117] offset:256
	s_nop 1
	v_mul_f32_e32 v114, v124, v124
	v_fmac_f32_e32 v114, v118, v118
	v_mul_f32_e32 v115, v125, v125
	v_add_f32_e32 v114, v114, v156
	v_fmac_f32_e32 v115, v119, v119
	v_add_f32_e32 v114, v115, v114
	v_mul_f32_e32 v115, v122, v122
	v_fmac_f32_e32 v115, v120, v120
	v_add_f32_e32 v114, v115, v114
	v_mul_f32_e32 v115, v123, v123
	v_fmac_f32_e32 v115, v121, v121
	v_add_f32_e32 v114, v115, v114
	v_mov_b32_e32 v115, v114
	s_nop 1
	v_permlane16_swap_b32_e32 v115, v114
	s_waitcnt lgkmcnt(0)
	v_add_f32_e32 v114, v114, v115
	v_mov_b32_e32 v115, v114
	s_nop 1
	v_permlane32_swap_b32_e32 v115, v114
	s_and_saveexec_b64 s[24:25], s[4:5]
	s_cbranch_execz .LBB0_1106
	s_waitcnt lgkmcnt(0)
	v_add_f32_e32 v116, v114, v115
	v_lshlrev_b64 v[114:115], 6, v[148:149]
	v_lshl_add_u64 v[114:115], s[38:39], 0, v[114:115]
	v_lshl_add_u64 v[114:115], s[48:49], 2, v[114:115]
	s_lshl_b32 s28, s53, 2
	s_mov_b32 s29, s93
	v_lshl_add_u64 v[114:115], v[114:115], 0, s[28:29]
	flat_store_dword v[114:115], v116
; __device__ __forceinline__ u32x4 pack8(f32x4 a, f32x4 b) { u32x4 w; w.x = pk2(a[0], a[1]); w.y = pk2(a[2], a[3]); w.z = pk2(b[0], b[1]); w.w = pk2(b[2], b[3]); return w; }
; __device__ __forceinline__ void unpack8(u32x4 w, f32x4& a, f32x4& b) { a = (f32x4){bflo(w.x), bfhi(w.x), bflo(w.y), bfhi(w.y)}; b = (f32x4){bflo(w.z), bfhi(w.z), bflo(w.w), bfhi(w.w)}; }
;     __device__ __forceinline__ void operator()(const Acc& acc, const Unit& u, int wr, int wc, int fr, int fq, const RsCtx& rc) const {
;     ...
;             for (int m = 0; m < 4; ++m) { const int row = EPI_ROW(u, ai, wr, m, fr); float s = 0.f;
; #pragma unroll
;                 for (int bj = 0; bj < 2; ++bj) { const size_t off = (size_t)row * DM + u.pn * 256 + bj * 128 + wc * 32 + 8 * fq;
;                     f32x4 x0, x1; unpack8(*(const u32x4*)(XB + off), x0, x1);
;                     x0 = x0 + acc[ai][bj][m][0] * alpha; x1 = x1 + acc[ai][bj][m][1] * alpha;
;                     *(u32x4*)(XB + off) = pack8(x0, x1);
; #pragma unroll
;                     for (int e = 0; e < 4; ++e) s += x0[e] * x0[e] + x1[e] * x1[e]; }
;                 s += __shfl_xor(s, 16); s += __shfl_xor(s, 32);
;                 if (fq == 0) ssq_x[(size_t)row * 16 + u.pn * 4 + wc] = s;
;                 if (m == 3) asm volatile("" ::: "memory"); }
.LBB0_1106:
	s_or_b64 exec, exec, s[24:25]
	v_or_b32_e32 v114, 16, v148
	s_waitcnt lgkmcnt(0)
	v_ashrrev_i32_e32 v115, 31, v114
	v_lshlrev_b64 v[116:117], 11, v[114:115]
	v_lshl_add_u64 v[116:117], s[36:37], 0, v[116:117]
	v_lshl_add_u64 v[116:117], s[50:51], 1, v[116:117]
	v_lshl_add_u64 v[116:117], v[116:117], 0, s[92:93]
	v_lshl_add_u64 v[120:121], v[116:117], 0, v[0:1]
	v_mov_b64_e32 v[116:117], v[168:169]
	v_mov_b64_e32 v[118:119], v[170:171]
	s_waitcnt lgkmcnt(0)
	v_lshlrev_b32_e32 v122, 16, v116
	v_and_b32_e32 v123, 0xffff0000, v116
	v_lshlrev_b32_e32 v116, 16, v117
	v_and_b32_e32 v117, 0xffff0000, v117
	v_lshlrev_b32_e32 v124, 16, v118
	v_and_b32_e32 v125, 0xffff0000, v118
	v_lshlrev_b32_e32 v118, 16, v119
	v_and_b32_e32 v119, 0xffff0000, v119
	v_pk_fma_f32 v[112:113], v[142:143], v[112:113], v[116:117]
	v_pk_fma_f32 v[110:111], v[130:131], v[110:111], v[122:123]
	v_pk_fma_f32 v[116:117], v[142:143], v[108:109], v[118:119]
	v_pk_fma_f32 v[118:119], v[130:131], v[106:107], v[124:125]
	v_cvt_pk_bf16_f32 v106, v110, v111
	v_cvt_pk_bf16_f32 v107, v112, v113
	v_cvt_pk_bf16_f32 v108, v118, v119
	v_cvt_pk_bf16_f32 v109, v116, v117
	flat_store_dwordx4 v[120:121], v[106:109]
	s_nop 1
	v_mul_f32_e32 v106, v118, v118
	v_mul_f32_e32 v107, v119, v119
	v_fmac_f32_e32 v106, v110, v110
	v_fmac_f32_e32 v107, v111, v111
	v_add_f32_e32 v106, v106, v107
	v_mul_f32_e32 v107, v116, v116
	v_fmac_f32_e32 v107, v112, v112
	v_add_f32_e32 v106, v107, v106
	v_mul_f32_e32 v107, v117, v117
	v_fmac_f32_e32 v107, v113, v113
	v_add_f32_e32 v116, v107, v106
	v_mov_b64_e32 v[106:107], v[172:173]
	v_mov_b64_e32 v[108:109], v[174:175]
	s_waitcnt lgkmcnt(0)
	v_lshlrev_b32_e32 v110, 16, v106
	v_and_b32_e32 v111, 0xffff0000, v106
	v_lshlrev_b32_e32 v106, 16, v107
	v_and_b32_e32 v107, 0xffff0000, v107
	v_lshlrev_b32_e32 v112, 16, v108
	v_and_b32_e32 v113, 0xffff0000, v108
	v_lshlrev_b32_e32 v108, 16, v109
	v_and_b32_e32 v109, 0xffff0000, v109
	v_pk_fma_f32 v[104:105], v[142:143], v[104:105], v[106:107]
	v_pk_fma_f32 v[102:103], v[130:131], v[102:103], v[110:111]
	v_pk_fma_f32 v[106:107], v[142:143], v[100:101], v[108:109]
	v_pk_fma_f32 v[108:109], v[130:131], v[98:99], v[112:113]
	v_cvt_pk_bf16_f32 v98, v102, v103
	v_cvt_pk_bf16_f32 v99, v104, v105
	v_cvt_pk_bf16_f32 v100, v108, v109
	v_cvt_pk_bf16_f32 v101, v106, v107
	flat_store_dwordx4 v[120:121], v[98:101] offset:256
	s_nop 1
	v_mul_f32_e32 v98, v108, v108
	v_fmac_f32_e32 v98, v102, v102
	v_mul_f32_e32 v99, v109, v109
	v_add_f32_e32 v98, v98, v116
	v_fmac_f32_e32 v99, v103, v103
	v_add_f32_e32 v98, v99, v98
	v_mul_f32_e32 v99, v106, v106
	v_fmac_f32_e32 v99, v104, v104
	v_add_f32_e32 v98, v99, v98
	v_mul_f32_e32 v99, v107, v107
	v_fmac_f32_e32 v99, v105, v105
	v_add_f32_e32 v98, v99, v98
	v_mov_b32_e32 v99, v98
	s_nop 1
	v_permlane16_swap_b32_e32 v99, v98
	s_waitcnt lgkmcnt(0)
	v_add_f32_e32 v98, v98, v99
	v_mov_b32_e32 v99, v98
	s_nop 1
	v_permlane32_swap_b32_e32 v99, v98
	s_and_saveexec_b64 s[24:25], s[4:5]
	s_cbranch_execz .LBB0_1108
	s_waitcnt lgkmcnt(0)
	v_add_f32_e32 v100, v98, v99
	v_lshlrev_b64 v[98:99], 6, v[114:115]
	v_lshl_add_u64 v[98:99], s[38:39], 0, v[98:99]
	v_lshl_add_u64 v[98:99], s[48:49], 2, v[98:99]
	s_lshl_b32 s28, s53, 2
	s_mov_b32 s29, s93
	v_lshl_add_u64 v[98:99], v[98:99], 0, s[28:29]
	flat_store_dword v[98:99], v100
.LBB0_1108:
	s_or_b64 exec, exec, s[24:25]
	v_or_b32_e32 v98, 32, v148
	s_waitcnt lgkmcnt(0)
	v_ashrrev_i32_e32 v99, 31, v98
	v_lshlrev_b64 v[100:101], 11, v[98:99]
	v_lshl_add_u64 v[100:101], s[36:37], 0, v[100:101]
	v_lshl_add_u64 v[100:101], s[50:51], 1, v[100:101]
	v_lshl_add_u64 v[100:101], v[100:101], 0, s[92:93]
	v_lshl_add_u64 v[104:105], v[100:101], 0, v[0:1]
	v_mov_b64_e32 v[100:101], v[176:177]
	v_mov_b64_e32 v[102:103], v[178:179]
	s_waitcnt lgkmcnt(0)
	v_lshlrev_b32_e32 v106, 16, v100
	v_and_b32_e32 v107, 0xffff0000, v100
	v_lshlrev_b32_e32 v100, 16, v101
	v_and_b32_e32 v101, 0xffff0000, v101
	v_lshlrev_b32_e32 v108, 16, v102
	v_and_b32_e32 v109, 0xffff0000, v102
	v_lshlrev_b32_e32 v102, 16, v103
	v_and_b32_e32 v103, 0xffff0000, v103
	v_pk_fma_f32 v[96:97], v[142:143], v[96:97], v[100:101]
	v_pk_fma_f32 v[94:95], v[130:131], v[94:95], v[106:107]
	v_pk_fma_f32 v[100:101], v[142:143], v[92:93], v[102:103]
	v_pk_fma_f32 v[102:103], v[130:131], v[90:91], v[108:109]
	v_cvt_pk_bf16_f32 v90, v94, v95
	v_cvt_pk_bf16_f32 v91, v96, v97
	v_cvt_pk_bf16_f32 v92, v102, v103
	v_cvt_pk_bf16_f32 v93, v100, v101
	flat_store_dwordx4 v[104:105], v[90:93]
	s_nop 1
	v_mul_f32_e32 v90, v102, v102
	v_mul_f32_e32 v91, v103, v103
	v_fmac_f32_e32 v90, v94, v94
	v_fmac_f32_e32 v91, v95, v95
	v_add_f32_e32 v90, v90, v91
	v_mul_f32_e32 v91, v100, v100
	v_fmac_f32_e32 v91, v96, v96
	v_add_f32_e32 v90, v91, v90
	v_mul_f32_e32 v91, v101, v101
	v_fmac_f32_e32 v91, v97, v97
	v_add_f32_e32 v100, v91, v90
	v_mov_b64_e32 v[90:91], v[180:181]
	v_mov_b64_e32 v[92:93], v[182:183]
	s_waitcnt lgkmcnt(0)
	v_lshlrev_b32_e32 v94, 16, v90
	v_and_b32_e32 v95, 0xffff0000, v90
	v_lshlrev_b32_e32 v90, 16, v91
	v_and_b32_e32 v91, 0xffff0000, v91
	v_lshlrev_b32_e32 v96, 16, v92
	v_and_b32_e32 v97, 0xffff0000, v92
	v_lshlrev_b32_e32 v92, 16, v93
	v_and_b32_e32 v93, 0xffff0000, v93
	v_pk_fma_f32 v[88:89], v[142:143], v[88:89], v[90:91]
	v_pk_fma_f32 v[86:87], v[130:131], v[86:87], v[94:95]
	v_pk_fma_f32 v[90:91], v[142:143], v[84:85], v[92:93]
	v_pk_fma_f32 v[92:93], v[130:131], v[82:83], v[96:97]
	v_cvt_pk_bf16_f32 v82, v86, v87
	v_cvt_pk_bf16_f32 v83, v88, v89
	v_cvt_pk_bf16_f32 v84, v92, v93
	v_cvt_pk_bf16_f32 v85, v90, v91
	flat_store_dwordx4 v[104:105], v[82:85] offset:256
	s_nop 1
	v_mul_f32_e32 v82, v92, v92
	v_fmac_f32_e32 v82, v86, v86
	v_mul_f32_e32 v83, v93, v93
	v_add_f32_e32 v82, v82, v100
	v_fmac_f32_e32 v83, v87, v87
	v_add_f32_e32 v82, v83, v82
	v_mul_f32_e32 v83, v90, v90
	v_fmac_f32_e32 v83, v88, v88
	v_add_f32_e32 v82, v83, v82
	v_mul_f32_e32 v83, v91, v91
	v_fmac_f32_e32 v83, v89, v89
	v_add_f32_e32 v82, v83, v82
	v_mov_b32_e32 v83, v82
	s_nop 1
	v_permlane16_swap_b32_e32 v83, v82
	s_waitcnt lgkmcnt(0)
	v_add_f32_e32 v82, v82, v83
	v_mov_b32_e32 v83, v82
	s_nop 1
	v_permlane32_swap_b32_e32 v83, v82
	s_and_saveexec_b64 s[24:25], s[4:5]
	s_cbranch_execz .LBB0_1110
	s_waitcnt lgkmcnt(0)
	v_add_f32_e32 v84, v82, v83
	v_lshlrev_b64 v[82:83], 6, v[98:99]
	v_lshl_add_u64 v[82:83], s[38:39], 0, v[82:83]
	v_lshl_add_u64 v[82:83], s[48:49], 2, v[82:83]
	s_lshl_b32 s28, s53, 2
	s_mov_b32 s29, s93
	v_lshl_add_u64 v[82:83], v[82:83], 0, s[28:29]
	flat_store_dword v[82:83], v84
; __device__ __forceinline__ u32x4 pack8(f32x4 a, f32x4 b) { u32x4 w; w.x = pk2(a[0], a[1]); w.y = pk2(a[2], a[3]); w.z = pk2(b[0], b[1]); w.w = pk2(b[2], b[3]); return w; }
; __device__ __forceinline__ void unpack8(u32x4 w, f32x4& a, f32x4& b) { a = (f32x4){bflo(w.x), bfhi(w.x), bflo(w.y), bfhi(w.y)}; b = (f32x4){bflo(w.z), bfhi(w.z), bflo(w.w), bfhi(w.w)}; }
;     __device__ __forceinline__ void operator()(const Acc& acc, const Unit& u, int wr, int wc, int fr, int fq, const RsCtx& rc) const {
;     ...
;             for (int m = 0; m < 4; ++m) { const int row = EPI_ROW(u, ai, wr, m, fr); float s = 0.f;
; #pragma unroll
;                 for (int bj = 0; bj < 2; ++bj) { const size_t off = (size_t)row * DM + u.pn * 256 + bj * 128 + wc * 32 + 8 * fq;
;                     f32x4 x0, x1; unpack8(*(const u32x4*)(XB + off), x0, x1);
;                     x0 = x0 + acc[ai][bj][m][0] * alpha; x1 = x1 + acc[ai][bj][m][1] * alpha;
;                     *(u32x4*)(XB + off) = pack8(x0, x1);
; #pragma unroll
;                     for (int e = 0; e < 4; ++e) s += x0[e] * x0[e] + x1[e] * x1[e]; }
;                 s += __shfl_xor(s, 16); s += __shfl_xor(s, 32);
;                 if (fq == 0) ssq_x[(size_t)row * 16 + u.pn * 4 + wc] = s;
;                 if (m == 3) asm volatile("" ::: "memory"); }
.LBB0_1110:
	s_or_b64 exec, exec, s[24:25]
	v_or_b32_e32 v82, 48, v148
	s_waitcnt lgkmcnt(0)
	v_ashrrev_i32_e32 v83, 31, v82
	v_lshlrev_b64 v[84:85], 11, v[82:83]
	v_lshl_add_u64 v[84:85], s[36:37], 0, v[84:85]
	v_lshl_add_u64 v[84:85], s[50:51], 1, v[84:85]
	v_lshl_add_u64 v[84:85], v[84:85], 0, s[92:93]
	v_lshl_add_u64 v[88:89], v[84:85], 0, v[0:1]
	v_mov_b64_e32 v[84:85], v[184:185]
	v_mov_b64_e32 v[86:87], v[186:187]
	s_waitcnt lgkmcnt(0)
	v_lshlrev_b32_e32 v90, 16, v84
	v_and_b32_e32 v91, 0xffff0000, v84
	v_lshlrev_b32_e32 v84, 16, v85
	v_and_b32_e32 v85, 0xffff0000, v85
	v_lshlrev_b32_e32 v92, 16, v86
	v_and_b32_e32 v93, 0xffff0000, v86
	v_lshlrev_b32_e32 v86, 16, v87
	v_and_b32_e32 v87, 0xffff0000, v87
	v_pk_fma_f32 v[80:81], v[142:143], v[80:81], v[84:85]
	v_pk_fma_f32 v[78:79], v[130:131], v[78:79], v[90:91]
	v_pk_fma_f32 v[84:85], v[142:143], v[76:77], v[86:87]
	v_pk_fma_f32 v[86:87], v[130:131], v[74:75], v[92:93]
	v_cvt_pk_bf16_f32 v74, v78, v79
	v_cvt_pk_bf16_f32 v75, v80, v81
	v_cvt_pk_bf16_f32 v76, v86, v87
	v_cvt_pk_bf16_f32 v77, v84, v85
	flat_store_dwordx4 v[88:89], v[74:77]
	s_nop 1
	v_mul_f32_e32 v74, v86, v86
	v_mul_f32_e32 v75, v87, v87
	v_fmac_f32_e32 v74, v78, v78
	v_fmac_f32_e32 v75, v79, v79
	v_add_f32_e32 v74, v74, v75
	v_mul_f32_e32 v75, v84, v84
	v_fmac_f32_e32 v75, v80, v80
	v_add_f32_e32 v74, v75, v74
	v_mul_f32_e32 v75, v85, v85
	v_fmac_f32_e32 v75, v81, v81
	v_add_f32_e32 v84, v75, v74
	v_mov_b64_e32 v[74:75], v[188:189]
	v_mov_b64_e32 v[76:77], v[190:191]
	s_waitcnt lgkmcnt(0)
	v_lshlrev_b32_e32 v78, 16, v74
	v_and_b32_e32 v79, 0xffff0000, v74
	v_lshlrev_b32_e32 v74, 16, v75
	v_and_b32_e32 v75, 0xffff0000, v75
	v_lshlrev_b32_e32 v80, 16, v76
	v_and_b32_e32 v81, 0xffff0000, v76
	v_lshlrev_b32_e32 v76, 16, v77
	v_and_b32_e32 v77, 0xffff0000, v77
	v_pk_fma_f32 v[72:73], v[142:143], v[72:73], v[74:75]
	v_pk_fma_f32 v[70:71], v[130:131], v[70:71], v[78:79]
	v_pk_fma_f32 v[74:75], v[142:143], v[68:69], v[76:77]
	v_pk_fma_f32 v[76:77], v[130:131], v[66:67], v[80:81]
	v_cvt_pk_bf16_f32 v66, v70, v71
	v_cvt_pk_bf16_f32 v67, v72, v73
	v_cvt_pk_bf16_f32 v68, v76, v77
	v_cvt_pk_bf16_f32 v69, v74, v75
	flat_store_dwordx4 v[88:89], v[66:69] offset:256
	s_nop 1
	v_mul_f32_e32 v66, v76, v76
	v_fmac_f32_e32 v66, v70, v70
	v_mul_f32_e32 v67, v77, v77
	v_add_f32_e32 v66, v66, v84
	v_fmac_f32_e32 v67, v71, v71
	v_add_f32_e32 v66, v67, v66
	v_mul_f32_e32 v67, v74, v74
	v_fmac_f32_e32 v67, v72, v72
	v_add_f32_e32 v66, v67, v66
	v_mul_f32_e32 v67, v75, v75
	v_fmac_f32_e32 v67, v73, v73
	v_add_f32_e32 v66, v67, v66
	v_mov_b32_e32 v67, v66
	s_nop 1
	v_permlane16_swap_b32_e32 v67, v66
	s_waitcnt lgkmcnt(0)
	v_add_f32_e32 v66, v66, v67
	v_mov_b32_e32 v67, v66
	s_nop 1
	v_permlane32_swap_b32_e32 v67, v66
	s_and_saveexec_b64 s[24:25], s[4:5]
	s_cbranch_execz .LBB0_1112
	s_waitcnt lgkmcnt(0)
	v_add_f32_e32 v68, v66, v67
	v_lshlrev_b64 v[66:67], 6, v[82:83]
	v_lshl_add_u64 v[66:67], s[38:39], 0, v[66:67]
	v_lshl_add_u64 v[66:67], s[48:49], 2, v[66:67]
	s_lshl_b32 s28, s53, 2
	s_mov_b32 s29, s93
	v_lshl_add_u64 v[66:67], v[66:67], 0, s[28:29]
	flat_store_dword v[66:67], v68
.LBB0_1112:
	s_or_b64 exec, exec, s[24:25]
	v_add_u32_e32 v66, 0x80, v148
	s_waitcnt lgkmcnt(0)
	v_ashrrev_i32_e32 v67, 31, v66
	v_lshlrev_b64 v[68:69], 11, v[66:67]
	v_lshl_add_u64 v[68:69], s[36:37], 0, v[68:69]
	v_lshl_add_u64 v[68:69], s[50:51], 1, v[68:69]
	v_lshl_add_u64 v[68:69], v[68:69], 0, s[92:93]
	v_lshl_add_u64 v[72:73], v[68:69], 0, v[0:1]
	v_mov_b64_e32 v[68:69], v[192:193]
	v_mov_b64_e32 v[70:71], v[194:195]
	s_waitcnt lgkmcnt(0)
	v_lshlrev_b32_e32 v74, 16, v68
	v_and_b32_e32 v75, 0xffff0000, v68
	v_lshlrev_b32_e32 v68, 16, v69
	v_and_b32_e32 v69, 0xffff0000, v69
	v_lshlrev_b32_e32 v76, 16, v70
	v_and_b32_e32 v77, 0xffff0000, v70
	v_lshlrev_b32_e32 v70, 16, v71
	v_and_b32_e32 v71, 0xffff0000, v71
	v_pk_fma_f32 v[64:65], v[142:143], v[64:65], v[68:69]
	v_pk_fma_f32 v[62:63], v[130:131], v[62:63], v[74:75]
	v_pk_fma_f32 v[68:69], v[142:143], v[60:61], v[70:71]
	v_pk_fma_f32 v[70:71], v[130:131], v[58:59], v[76:77]
	v_cvt_pk_bf16_f32 v58, v62, v63
	v_cvt_pk_bf16_f32 v59, v64, v65
	v_cvt_pk_bf16_f32 v60, v70, v71
	v_cvt_pk_bf16_f32 v61, v68, v69
	flat_store_dwordx4 v[72:73], v[58:61]
	s_nop 1
	v_mul_f32_e32 v58, v70, v70
	v_mul_f32_e32 v59, v71, v71
	v_fmac_f32_e32 v58, v62, v62
	v_fmac_f32_e32 v59, v63, v63
	v_add_f32_e32 v58, v58, v59
	v_mul_f32_e32 v59, v68, v68
	v_fmac_f32_e32 v59, v64, v64
	v_add_f32_e32 v58, v59, v58
	v_mul_f32_e32 v59, v69, v69
	v_fmac_f32_e32 v59, v65, v65
	v_add_f32_e32 v68, v59, v58
	v_mov_b64_e32 v[58:59], v[206:207]
	v_mov_b64_e32 v[60:61], v[208:209]
	s_waitcnt lgkmcnt(0)
	v_lshlrev_b32_e32 v62, 16, v58
	v_and_b32_e32 v63, 0xffff0000, v58
	v_lshlrev_b32_e32 v58, 16, v59
	v_and_b32_e32 v59, 0xffff0000, v59
	v_lshlrev_b32_e32 v64, 16, v60
	v_and_b32_e32 v65, 0xffff0000, v60
	v_lshlrev_b32_e32 v60, 16, v61
	v_and_b32_e32 v61, 0xffff0000, v61
	v_pk_fma_f32 v[56:57], v[142:143], v[56:57], v[58:59]
	v_pk_fma_f32 v[54:55], v[130:131], v[54:55], v[62:63]
	v_pk_fma_f32 v[58:59], v[142:143], v[52:53], v[60:61]
	v_pk_fma_f32 v[60:61], v[130:131], v[50:51], v[64:65]
	v_cvt_pk_bf16_f32 v50, v54, v55
	v_cvt_pk_bf16_f32 v51, v56, v57
	v_cvt_pk_bf16_f32 v52, v60, v61
	v_cvt_pk_bf16_f32 v53, v58, v59
	flat_store_dwordx4 v[72:73], v[50:53] offset:256
	s_nop 1
	v_mul_f32_e32 v50, v60, v60
	v_fmac_f32_e32 v50, v54, v54
	v_mul_f32_e32 v51, v61, v61
	v_add_f32_e32 v50, v50, v68
	v_fmac_f32_e32 v51, v55, v55
	v_add_f32_e32 v50, v51, v50
	v_mul_f32_e32 v51, v58, v58
	v_fmac_f32_e32 v51, v56, v56
	v_add_f32_e32 v50, v51, v50
	v_mul_f32_e32 v51, v59, v59
	v_fmac_f32_e32 v51, v57, v57
	v_add_f32_e32 v50, v51, v50
	v_mov_b32_e32 v51, v50
	s_nop 1
	v_permlane16_swap_b32_e32 v51, v50
	s_waitcnt lgkmcnt(0)
	v_add_f32_e32 v50, v50, v51
	v_mov_b32_e32 v51, v50
	s_nop 1
	v_permlane32_swap_b32_e32 v51, v50
	s_and_saveexec_b64 s[24:25], s[4:5]
	s_cbranch_execz .LBB0_1114
	s_waitcnt lgkmcnt(0)
	v_add_f32_e32 v52, v50, v51
	v_lshlrev_b64 v[50:51], 6, v[66:67]
	v_lshl_add_u64 v[50:51], s[38:39], 0, v[50:51]
	v_lshl_add_u64 v[50:51], s[48:49], 2, v[50:51]
	s_lshl_b32 s28, s53, 2
	s_mov_b32 s29, s93
	v_lshl_add_u64 v[50:51], v[50:51], 0, s[28:29]
	flat_store_dword v[50:51], v52
; __device__ __forceinline__ u32x4 pack8(f32x4 a, f32x4 b) { u32x4 w; w.x = pk2(a[0], a[1]); w.y = pk2(a[2], a[3]); w.z = pk2(b[0], b[1]); w.w = pk2(b[2], b[3]); return w; }
; __device__ __forceinline__ void unpack8(u32x4 w, f32x4& a, f32x4& b) { a = (f32x4){bflo(w.x), bfhi(w.x), bflo(w.y), bfhi(w.y)}; b = (f32x4){bflo(w.z), bfhi(w.z), bflo(w.w), bfhi(w.w)}; }
;     __device__ __forceinline__ void operator()(const Acc& acc, const Unit& u, int wr, int wc, int fr, int fq, const RsCtx& rc) const {
;     ...
;             for (int m = 0; m < 4; ++m) { const int row = EPI_ROW(u, ai, wr, m, fr); float s = 0.f;
; #pragma unroll
;                 for (int bj = 0; bj < 2; ++bj) { const size_t off = (size_t)row * DM + u.pn * 256 + bj * 128 + wc * 32 + 8 * fq;
;                     f32x4 x0, x1; unpack8(*(const u32x4*)(XB + off), x0, x1);
;                     x0 = x0 + acc[ai][bj][m][0] * alpha; x1 = x1 + acc[ai][bj][m][1] * alpha;
;                     *(u32x4*)(XB + off) = pack8(x0, x1);
; #pragma unroll
;                     for (int e = 0; e < 4; ++e) s += x0[e] * x0[e] + x1[e] * x1[e]; }
;                 s += __shfl_xor(s, 16); s += __shfl_xor(s, 32);
;                 if (fq == 0) ssq_x[(size_t)row * 16 + u.pn * 4 + wc] = s;
;                 if (m == 3) asm volatile("" ::: "memory"); }
.LBB0_1114:
	s_or_b64 exec, exec, s[24:25]
	v_add_u32_e32 v50, 0x90, v148
	s_waitcnt lgkmcnt(0)
	v_ashrrev_i32_e32 v51, 31, v50
	v_lshlrev_b64 v[52:53], 11, v[50:51]
	v_lshl_add_u64 v[52:53], s[36:37], 0, v[52:53]
	v_lshl_add_u64 v[52:53], s[50:51], 1, v[52:53]
	v_lshl_add_u64 v[52:53], v[52:53], 0, s[92:93]
	v_lshl_add_u64 v[56:57], v[52:53], 0, v[0:1]
	v_mov_b64_e32 v[52:53], v[218:219]
	v_mov_b64_e32 v[54:55], v[220:221]
	s_waitcnt lgkmcnt(0)
	v_lshlrev_b32_e32 v58, 16, v52
	v_and_b32_e32 v59, 0xffff0000, v52
	v_lshlrev_b32_e32 v52, 16, v53
	v_and_b32_e32 v53, 0xffff0000, v53
	v_lshlrev_b32_e32 v60, 16, v54
	v_and_b32_e32 v61, 0xffff0000, v54
	v_lshlrev_b32_e32 v54, 16, v55
	v_and_b32_e32 v55, 0xffff0000, v55
	v_pk_fma_f32 v[48:49], v[142:143], v[48:49], v[52:53]
	v_pk_fma_f32 v[46:47], v[130:131], v[46:47], v[58:59]
	v_pk_fma_f32 v[52:53], v[142:143], v[44:45], v[54:55]
	v_pk_fma_f32 v[54:55], v[130:131], v[42:43], v[60:61]
	v_cvt_pk_bf16_f32 v42, v46, v47
	v_cvt_pk_bf16_f32 v43, v48, v49
	v_cvt_pk_bf16_f32 v44, v54, v55
	v_cvt_pk_bf16_f32 v45, v52, v53
	flat_store_dwordx4 v[56:57], v[42:45]
	s_nop 1
	v_mul_f32_e32 v42, v54, v54
	v_mul_f32_e32 v43, v55, v55
	v_fmac_f32_e32 v42, v46, v46
	v_fmac_f32_e32 v43, v47, v47
	v_add_f32_e32 v42, v42, v43
	v_mul_f32_e32 v43, v52, v52
	v_fmac_f32_e32 v43, v48, v48
	v_add_f32_e32 v42, v43, v42
	v_mul_f32_e32 v43, v53, v53
	v_fmac_f32_e32 v43, v49, v49
	v_add_f32_e32 v52, v43, v42
	v_mov_b64_e32 v[42:43], v[232:233]
	v_mov_b64_e32 v[44:45], v[234:235]
	s_waitcnt lgkmcnt(0)
	v_lshlrev_b32_e32 v46, 16, v42
	v_and_b32_e32 v47, 0xffff0000, v42
	v_lshlrev_b32_e32 v42, 16, v43
	v_and_b32_e32 v43, 0xffff0000, v43
	v_lshlrev_b32_e32 v48, 16, v44
	v_and_b32_e32 v49, 0xffff0000, v44
	v_lshlrev_b32_e32 v44, 16, v45
	v_and_b32_e32 v45, 0xffff0000, v45
	v_pk_fma_f32 v[40:41], v[142:143], v[40:41], v[42:43]
	v_pk_fma_f32 v[38:39], v[130:131], v[38:39], v[46:47]
	v_pk_fma_f32 v[42:43], v[142:143], v[36:37], v[44:45]
	v_pk_fma_f32 v[44:45], v[130:131], v[34:35], v[48:49]
	v_cvt_pk_bf16_f32 v34, v38, v39
	v_cvt_pk_bf16_f32 v35, v40, v41
	v_cvt_pk_bf16_f32 v36, v44, v45
	v_cvt_pk_bf16_f32 v37, v42, v43
	flat_store_dwordx4 v[56:57], v[34:37] offset:256
	s_nop 1
	v_mul_f32_e32 v34, v44, v44
	v_fmac_f32_e32 v34, v38, v38
	v_mul_f32_e32 v35, v45, v45
	v_add_f32_e32 v34, v34, v52
	v_fmac_f32_e32 v35, v39, v39
	v_add_f32_e32 v34, v35, v34
	v_mul_f32_e32 v35, v42, v42
	v_fmac_f32_e32 v35, v40, v40
	v_add_f32_e32 v34, v35, v34
	v_mul_f32_e32 v35, v43, v43
	v_fmac_f32_e32 v35, v41, v41
	v_add_f32_e32 v34, v35, v34
	v_mov_b32_e32 v35, v34
	s_nop 1
	v_permlane16_swap_b32_e32 v35, v34
	s_waitcnt lgkmcnt(0)
	v_add_f32_e32 v34, v34, v35
	v_mov_b32_e32 v35, v34
	s_nop 1
	v_permlane32_swap_b32_e32 v35, v34
	s_and_saveexec_b64 s[24:25], s[4:5]
	s_cbranch_execz .LBB0_1116
	s_waitcnt lgkmcnt(0)
	v_add_f32_e32 v36, v34, v35
	v_lshlrev_b64 v[34:35], 6, v[50:51]
	v_lshl_add_u64 v[34:35], s[38:39], 0, v[34:35]
	v_lshl_add_u64 v[34:35], s[48:49], 2, v[34:35]
	s_lshl_b32 s28, s53, 2
	s_mov_b32 s29, s93
	v_lshl_add_u64 v[34:35], v[34:35], 0, s[28:29]
	flat_store_dword v[34:35], v36
; __device__ __forceinline__ u32x4 pack8(f32x4 a, f32x4 b) { u32x4 w; w.x = pk2(a[0], a[1]); w.y = pk2(a[2], a[3]); w.z = pk2(b[0], b[1]); w.w = pk2(b[2], b[3]); return w; }
; __device__ __forceinline__ void unpack8(u32x4 w, f32x4& a, f32x4& b) { a = (f32x4){bflo(w.x), bfhi(w.x), bflo(w.y), bfhi(w.y)}; b = (f32x4){bflo(w.z), bfhi(w.z), bflo(w.w), bfhi(w.w)}; }
;     __device__ __forceinline__ void operator()(const Acc& acc, const Unit& u, int wr, int wc, int fr, int fq, const RsCtx& rc) const {
;     ...
;             for (int m = 0; m < 4; ++m) { const int row = EPI_ROW(u, ai, wr, m, fr); float s = 0.f;
; #pragma unroll
;                 for (int bj = 0; bj < 2; ++bj) { const size_t off = (size_t)row * DM + u.pn * 256 + bj * 128 + wc * 32 + 8 * fq;
;                     f32x4 x0, x1; unpack8(*(const u32x4*)(XB + off), x0, x1);
;                     x0 = x0 + acc[ai][bj][m][0] * alpha; x1 = x1 + acc[ai][bj][m][1] * alpha;
;                     *(u32x4*)(XB + off) = pack8(x0, x1);
; #pragma unroll
;                     for (int e = 0; e < 4; ++e) s += x0[e] * x0[e] + x1[e] * x1[e]; }
;                 s += __shfl_xor(s, 16); s += __shfl_xor(s, 32);
;                 if (fq == 0) ssq_x[(size_t)row * 16 + u.pn * 4 + wc] = s;
;                 if (m == 3) asm volatile("" ::: "memory"); }
.LBB0_1116:
	s_or_b64 exec, exec, s[24:25]
	v_add_u32_e32 v34, 0xa0, v148
	s_waitcnt lgkmcnt(0)
	v_ashrrev_i32_e32 v35, 31, v34
	v_lshlrev_b64 v[36:37], 11, v[34:35]
	v_lshl_add_u64 v[36:37], s[36:37], 0, v[36:37]
	v_lshl_add_u64 v[36:37], s[50:51], 1, v[36:37]
	v_lshl_add_u64 v[36:37], v[36:37], 0, s[92:93]
	v_lshl_add_u64 v[40:41], v[36:37], 0, v[0:1]
	v_mov_b64_e32 v[36:37], v[236:237]
	v_mov_b64_e32 v[38:39], v[238:239]
	s_waitcnt lgkmcnt(0)
	v_lshlrev_b32_e32 v42, 16, v36
	v_and_b32_e32 v43, 0xffff0000, v36
	v_lshlrev_b32_e32 v36, 16, v37
	v_and_b32_e32 v37, 0xffff0000, v37
	v_lshlrev_b32_e32 v44, 16, v38
	v_and_b32_e32 v45, 0xffff0000, v38
	v_lshlrev_b32_e32 v38, 16, v39
	v_and_b32_e32 v39, 0xffff0000, v39
	v_pk_fma_f32 v[32:33], v[142:143], v[32:33], v[36:37]
	v_pk_fma_f32 v[30:31], v[130:131], v[30:31], v[42:43]
	v_pk_fma_f32 v[36:37], v[142:143], v[28:29], v[38:39]
	v_pk_fma_f32 v[38:39], v[130:131], v[26:27], v[44:45]
	v_cvt_pk_bf16_f32 v26, v30, v31
	v_cvt_pk_bf16_f32 v27, v32, v33
	v_cvt_pk_bf16_f32 v28, v38, v39
	v_cvt_pk_bf16_f32 v29, v36, v37
	flat_store_dwordx4 v[40:41], v[26:29]
	s_nop 1
	v_mul_f32_e32 v26, v38, v38
	v_mul_f32_e32 v27, v39, v39
	v_fmac_f32_e32 v26, v30, v30
	v_fmac_f32_e32 v27, v31, v31
	v_add_f32_e32 v26, v26, v27
	v_mul_f32_e32 v27, v36, v36
	v_fmac_f32_e32 v27, v32, v32
	v_add_f32_e32 v26, v27, v26
	v_mul_f32_e32 v27, v37, v37
	v_fmac_f32_e32 v27, v33, v33
	v_add_f32_e32 v36, v27, v26
	v_mov_b64_e32 v[26:27], v[240:241]
	v_mov_b64_e32 v[28:29], v[242:243]
	s_waitcnt lgkmcnt(0)
	v_lshlrev_b32_e32 v30, 16, v26
	v_and_b32_e32 v31, 0xffff0000, v26
	v_lshlrev_b32_e32 v26, 16, v27
	v_and_b32_e32 v27, 0xffff0000, v27
	v_lshlrev_b32_e32 v32, 16, v28
	v_and_b32_e32 v33, 0xffff0000, v28
	v_lshlrev_b32_e32 v28, 16, v29
	v_and_b32_e32 v29, 0xffff0000, v29
	v_pk_fma_f32 v[24:25], v[142:143], v[24:25], v[26:27]
	v_pk_fma_f32 v[22:23], v[130:131], v[22:23], v[30:31]
	v_pk_fma_f32 v[26:27], v[142:143], v[20:21], v[28:29]
	v_pk_fma_f32 v[28:29], v[130:131], v[18:19], v[32:33]
	v_cvt_pk_bf16_f32 v18, v22, v23
	v_cvt_pk_bf16_f32 v19, v24, v25
	v_cvt_pk_bf16_f32 v20, v28, v29
	v_cvt_pk_bf16_f32 v21, v26, v27
	flat_store_dwordx4 v[40:41], v[18:21] offset:256
	s_nop 1
	v_mul_f32_e32 v18, v28, v28
	v_fmac_f32_e32 v18, v22, v22
	v_mul_f32_e32 v19, v29, v29
	v_add_f32_e32 v18, v18, v36
	v_fmac_f32_e32 v19, v23, v23
	v_add_f32_e32 v18, v19, v18
	v_mul_f32_e32 v19, v26, v26
	v_fmac_f32_e32 v19, v24, v24
	v_add_f32_e32 v18, v19, v18
	v_mul_f32_e32 v19, v27, v27
	v_fmac_f32_e32 v19, v25, v25
	v_add_f32_e32 v18, v19, v18
	v_mov_b32_e32 v19, v18
	s_nop 1
	v_permlane16_swap_b32_e32 v19, v18
	s_waitcnt lgkmcnt(0)
	v_add_f32_e32 v18, v18, v19
	v_mov_b32_e32 v19, v18
	s_nop 1
	v_permlane32_swap_b32_e32 v19, v18
	s_and_saveexec_b64 s[24:25], s[4:5]
	s_cbranch_execz .LBB0_1118
	s_waitcnt lgkmcnt(0)
	v_add_f32_e32 v20, v18, v19
	v_lshlrev_b64 v[18:19], 6, v[34:35]
	v_lshl_add_u64 v[18:19], s[38:39], 0, v[18:19]
	v_lshl_add_u64 v[18:19], s[48:49], 2, v[18:19]
	s_lshl_b32 s28, s53, 2
	s_mov_b32 s29, s93
	v_lshl_add_u64 v[18:19], v[18:19], 0, s[28:29]
	flat_store_dword v[18:19], v20
.LBB0_1118:
	s_or_b64 exec, exec, s[24:25]
	v_add_u32_e32 v18, 0xb0, v148
	s_waitcnt lgkmcnt(0)
	v_ashrrev_i32_e32 v19, 31, v18
	v_lshlrev_b64 v[20:21], 11, v[18:19]
	v_lshl_add_u64 v[20:21], s[36:37], 0, v[20:21]
	v_lshl_add_u64 v[20:21], s[50:51], 1, v[20:21]
	v_lshl_add_u64 v[20:21], v[20:21], 0, s[92:93]
	v_lshl_add_u64 v[24:25], v[20:21], 0, v[0:1]
	v_mov_b64_e32 v[20:21], v[244:245]
	v_mov_b64_e32 v[22:23], v[246:247]
	s_waitcnt lgkmcnt(0)
	v_lshlrev_b32_e32 v26, 16, v20
	v_and_b32_e32 v27, 0xffff0000, v20
	v_lshlrev_b32_e32 v20, 16, v21
	v_and_b32_e32 v21, 0xffff0000, v21
	v_lshlrev_b32_e32 v28, 16, v22
	v_and_b32_e32 v29, 0xffff0000, v22
	v_lshlrev_b32_e32 v22, 16, v23
	v_and_b32_e32 v23, 0xffff0000, v23
	v_pk_fma_f32 v[16:17], v[142:143], v[16:17], v[20:21]
	v_pk_fma_f32 v[14:15], v[130:131], v[14:15], v[26:27]
	v_pk_fma_f32 v[20:21], v[142:143], v[12:13], v[22:23]
	v_pk_fma_f32 v[22:23], v[130:131], v[10:11], v[28:29]
	v_cvt_pk_bf16_f32 v10, v14, v15
	v_cvt_pk_bf16_f32 v11, v16, v17
	v_cvt_pk_bf16_f32 v12, v22, v23
	v_cvt_pk_bf16_f32 v13, v20, v21
	flat_store_dwordx4 v[24:25], v[10:13]
	v_mul_f32_e32 v0, v22, v22
	v_fmac_f32_e32 v0, v14, v14
	v_mul_f32_e32 v10, v23, v23
	v_fmac_f32_e32 v10, v15, v15
	v_add_f32_e32 v0, v0, v10
	v_mul_f32_e32 v10, v20, v20
	v_fmac_f32_e32 v10, v16, v16
	v_add_f32_e32 v0, v10, v0
	v_mul_f32_e32 v10, v21, v21
	v_fmac_f32_e32 v10, v17, v17
	v_add_f32_e32 v0, v10, v0
	v_mov_b64_e32 v[10:11], v[248:249]
	v_mov_b64_e32 v[12:13], v[250:251]
	s_waitcnt lgkmcnt(0)
	v_lshlrev_b32_e32 v14, 16, v10
	v_and_b32_e32 v15, 0xffff0000, v10
	v_lshlrev_b32_e32 v10, 16, v11
	v_and_b32_e32 v11, 0xffff0000, v11
	v_lshlrev_b32_e32 v16, 16, v12
	v_and_b32_e32 v17, 0xffff0000, v12
	v_lshlrev_b32_e32 v12, 16, v13
	v_and_b32_e32 v13, 0xffff0000, v13
	v_pk_fma_f32 v[8:9], v[142:143], v[8:9], v[10:11]
	v_pk_fma_f32 v[6:7], v[130:131], v[6:7], v[14:15]
	v_pk_fma_f32 v[10:11], v[142:143], v[4:5], v[12:13]
	v_pk_fma_f32 v[12:13], v[130:131], v[2:3], v[16:17]
	v_cvt_pk_bf16_f32 v2, v6, v7
	v_cvt_pk_bf16_f32 v3, v8, v9
	v_cvt_pk_bf16_f32 v4, v12, v13
	v_cvt_pk_bf16_f32 v5, v10, v11
	flat_store_dwordx4 v[24:25], v[2:5] offset:256
	s_nop 1
	v_mul_f32_e32 v2, v12, v12
	v_fmac_f32_e32 v2, v6, v6
	v_add_f32_e32 v0, v2, v0
	v_mul_f32_e32 v2, v13, v13
	v_fmac_f32_e32 v2, v7, v7
	v_add_f32_e32 v0, v2, v0
	v_mul_f32_e32 v2, v10, v10
	v_fmac_f32_e32 v2, v8, v8
	v_add_f32_e32 v0, v2, v0
	v_mul_f32_e32 v2, v11, v11
	v_fmac_f32_e32 v2, v9, v9
	v_add_f32_e32 v0, v2, v0
	v_mov_b32_e32 v2, v0
	s_nop 1
	v_permlane16_swap_b32_e32 v2, v0
	s_waitcnt lgkmcnt(0)
	v_add_f32_e32 v0, v0, v2
	v_mov_b32_e32 v2, v0
	s_nop 1
	v_permlane32_swap_b32_e32 v2, v0
	s_and_saveexec_b64 s[24:25], s[4:5]
	s_cbranch_execz .LBB0_1120
	s_waitcnt lgkmcnt(0)
	v_add_f32_e32 v0, v0, v2
	v_lshlrev_b64 v[2:3], 6, v[18:19]
	v_lshl_add_u64 v[2:3], s[38:39], 0, v[2:3]
	v_lshl_add_u64 v[2:3], s[48:49], 2, v[2:3]
	s_lshl_b32 s92, s53, 2
	v_lshl_add_u64 v[2:3], v[2:3], 0, s[92:93]
	flat_store_dword v[2:3], v0
